# GEMM k-loops: first-half LDS fragment reads hoisted right after the barrier (before the LDS-DMA block), second half after it
# baseline (speedup 1.0000x reference)
.LBB0_231:
	v_lshl_add_u64 v[100:101], v[80:81], 0, s[24:25]
	s_add_i32 s47, s48, 0x8000
	s_and_b32 s27, s48, 0x8000
	s_mov_b64 s[48:49], 0x2200080
	v_lshl_add_u64 v[102:103], v[82:83], 0, s[24:25]
	v_lshl_add_u64 v[104:105], v[100:101], 0, s[48:49]
	s_mov_b64 s[48:49], 0x700080
	v_lshl_add_u64 v[106:107], v[102:103], 0, s[48:49]
	s_mov_b64 s[48:49], 0x2211080
	v_lshl_add_u64 v[108:109], v[100:101], 0, s[48:49]
	s_mov_b64 s[48:49], 0x711080
	s_and_b32 s50, s47, 0x8000
	v_lshl_add_u64 v[110:111], v[102:103], 0, s[48:49]
	s_mov_b64 s[48:49], 0x2222080
	v_lshl_add_u64 v[112:113], v[100:101], 0, s[48:49]
	s_add_i32 s48, s27, 0
	s_add_i32 s27, s50, 0
	v_add_u32_e32 v116, s27, v84
	v_add_u32_e32 v117, 0x4000, v116
	v_readfirstlane_b32 s49, v116
	v_add_u32_e32 v118, 0x1000, v116
	v_readfirstlane_b32 s50, v117
	s_mov_b32 m0, s49
	s_waitcnt vmcnt(0) lgkmcnt(0)
	s_barrier
	v_add3_u32 v145, s48, v86, v87
	v_add3_u32 v232, s48, v87, v88
	v_add3_u32 v233, s48, v86, v89
	v_add3_u32 v234, s48, v88, v89
	ds_read_b128 v[168:171], v232
	ds_read_b128 v[164:167], v145 offset:16384
	ds_read_b128 v[172:175], v145 offset:18432
	ds_read_b128 v[188:191], v232 offset:2048
	ds_read_b128 v[176:179], v145 offset:20480
	ds_read_b128 v[180:183], v145 offset:22528
	ds_read_b128 v[184:187], v145 offset:24576
	ds_read_b128 v[124:127], v145 offset:26624
	ds_read_b128 v[128:131], v145 offset:28672
	ds_read_b128 v[132:135], v145 offset:30720
	v_add_u32_e32 v119, 0x5000, v116
	v_readfirstlane_b32 s51, v118
	global_load_lds_dwordx4 v[104:105], off
	s_mov_b32 m0, s50
	v_add_u32_e32 v120, 0x2000, v116
	v_readfirstlane_b32 s52, v119
	global_load_lds_dwordx4 v[106:107], off
	s_mov_b32 m0, s51
	v_add_u32_e32 v121, 0x6000, v116
	v_readfirstlane_b32 s53, v120
	global_load_lds_dwordx4 v[108:109], off
	s_mov_b32 m0, s52
	v_add_u32_e32 v122, 0x3000, v116
	v_readfirstlane_b32 s54, v121
	global_load_lds_dwordx4 v[110:111], off
	s_mov_b32 m0, s53
	v_lshl_add_u64 v[114:115], v[102:103], 0, s[12:13]
	v_add_u32_e32 v116, 0x7000, v116
	v_readfirstlane_b32 s55, v122
	global_load_lds_dwordx4 v[112:113], off
	s_mov_b32 m0, s54
	v_lshl_add_u64 v[100:101], v[100:101], 0, s[14:15]
	v_readfirstlane_b32 s56, v116
	global_load_lds_dwordx4 v[114:115], off
	s_mov_b32 m0, s55
	v_lshl_add_u64 v[102:103], v[102:103], 0, s[16:17]
	global_load_lds_dwordx4 v[100:101], off
	s_mov_b32 m0, s56
	global_load_lds_dwordx4 v[102:103], off
	ds_read_b128 v[224:227], v234
	ds_read_b128 v[192:195], v233 offset:16384
	ds_read_b128 v[196:199], v233 offset:18432
	ds_read_b128 v[228:231], v234 offset:2048
	ds_read_b128 v[200:203], v233 offset:20480
	ds_read_b128 v[204:207], v233 offset:22528
	ds_read_b128 v[208:211], v233 offset:24576
	ds_read_b128 v[212:215], v233 offset:26624
	ds_read_b128 v[216:219], v233 offset:28672
	ds_read_b128 v[220:223], v233 offset:30720
	s_add_u32 s24, s24, 0x80
	s_addc_u32 s25, s25, 0
	s_cmpk_eq_i32 s24, 0x780
	s_mov_b32 s48, s47
	s_waitcnt lgkmcnt(15)
	v_mfma_f32_16x16x32_bf16 v[60:63], v[164:167], v[168:171], v[60:63]
	v_mfma_f32_16x16x32_bf16 v[56:59], v[172:175], v[168:171], v[56:59]
	v_mfma_f32_16x16x32_bf16 v[24:27], v[164:167], v[188:191], v[24:27]
	v_mfma_f32_16x16x32_bf16 v[20:23], v[172:175], v[188:191], v[20:23]
	v_mfma_f32_16x16x32_bf16 v[52:55], v[176:179], v[168:171], v[52:55]
	v_mfma_f32_16x16x32_bf16 v[16:19], v[176:179], v[188:191], v[16:19]
	s_waitcnt lgkmcnt(14)
	v_mfma_f32_16x16x32_bf16 v[48:51], v[180:183], v[168:171], v[48:51]
	v_mfma_f32_16x16x32_bf16 v[12:15], v[180:183], v[188:191], v[12:15]
	s_waitcnt lgkmcnt(13)
	v_mfma_f32_16x16x32_bf16 v[44:47], v[184:187], v[168:171], v[44:47]
	v_mfma_f32_16x16x32_bf16 v[8:11], v[184:187], v[188:191], v[8:11]
	s_waitcnt lgkmcnt(12)
	v_mfma_f32_16x16x32_bf16 v[40:43], v[124:127], v[168:171], v[40:43]
	v_mfma_f32_16x16x32_bf16 v[4:7], v[124:127], v[188:191], v[4:7]
	s_waitcnt lgkmcnt(11)
	v_mfma_f32_16x16x32_bf16 v[36:39], v[128:131], v[168:171], v[36:39]
	v_mfma_f32_16x16x32_bf16 v[0:3], v[128:131], v[188:191], v[0:3]
	s_waitcnt lgkmcnt(10)
	v_mfma_f32_16x16x32_bf16 v[32:35], v[132:135], v[168:171], v[32:35]
	v_mfma_f32_16x16x32_bf16 v[28:31], v[132:135], v[188:191], v[28:31]
	s_waitcnt lgkmcnt(8)
	v_mfma_f32_16x16x32_bf16 v[60:63], v[192:195], v[224:227], v[60:63]
	s_waitcnt lgkmcnt(7)
	v_mfma_f32_16x16x32_bf16 v[56:59], v[196:199], v[224:227], v[56:59]
	s_waitcnt lgkmcnt(6)
	v_mfma_f32_16x16x32_bf16 v[24:27], v[192:195], v[228:231], v[24:27]
	v_mfma_f32_16x16x32_bf16 v[20:23], v[196:199], v[228:231], v[20:23]
	s_waitcnt lgkmcnt(5)
	v_mfma_f32_16x16x32_bf16 v[52:55], v[200:203], v[224:227], v[52:55]
	v_mfma_f32_16x16x32_bf16 v[16:19], v[200:203], v[228:231], v[16:19]
	s_waitcnt lgkmcnt(4)
	v_mfma_f32_16x16x32_bf16 v[48:51], v[204:207], v[224:227], v[48:51]
	v_mfma_f32_16x16x32_bf16 v[12:15], v[204:207], v[228:231], v[12:15]
	s_waitcnt lgkmcnt(3)
	v_mfma_f32_16x16x32_bf16 v[44:47], v[208:211], v[224:227], v[44:47]
	v_mfma_f32_16x16x32_bf16 v[8:11], v[208:211], v[228:231], v[8:11]
	s_waitcnt lgkmcnt(2)
	v_mfma_f32_16x16x32_bf16 v[40:43], v[212:215], v[224:227], v[40:43]
	v_mfma_f32_16x16x32_bf16 v[4:7], v[212:215], v[228:231], v[4:7]
	s_waitcnt lgkmcnt(1)
	v_mfma_f32_16x16x32_bf16 v[36:39], v[216:219], v[224:227], v[36:39]
	v_mfma_f32_16x16x32_bf16 v[0:3], v[216:219], v[228:231], v[0:3]
	s_waitcnt lgkmcnt(0)
	v_mfma_f32_16x16x32_bf16 v[32:35], v[220:223], v[224:227], v[32:35]
	v_mfma_f32_16x16x32_bf16 v[28:31], v[220:223], v[228:231], v[28:31]
	s_cbranch_scc0 .LBB0_231
	v_add_u32_e32 v64, s27, v86
	v_add_u32_e32 v136, v64, v87
	v_add3_u32 v108, s27, v87, v88
	s_waitcnt vmcnt(0)
	s_barrier
	ds_read_b128 v[80:83], v136 offset:16384
	ds_read_b128 v[100:103], v136 offset:18432
	ds_read_b128 v[104:107], v108
	ds_read_b128 v[108:111], v108 offset:2048
	ds_read_b128 v[112:115], v136 offset:20480
	ds_read_b128 v[116:119], v136 offset:22528
	ds_read_b128 v[128:131], v136 offset:28672
	s_waitcnt lgkmcnt(2)
	v_mfma_f32_16x16x32_bf16 v[120:123], v[112:115], v[104:107], v[52:55]
	s_nop 2
	ds_read_b128 v[52:55], v136 offset:24576
	ds_read_b128 v[124:127], v136 offset:26624
	s_cmp_gt_i32 s26, 11
	s_waitcnt lgkmcnt(0)
	v_mfma_f32_16x16x32_bf16 v[132:135], v[124:127], v[104:107], v[40:43]
	s_nop 2
	ds_read_b128 v[40:43], v136 offset:30720
	s_cselect_b64 s[24:25], -1, 0
	s_cmp_lt_i32 s26, 12
	v_mfma_f32_16x16x32_bf16 v[60:63], v[80:83], v[104:107], v[60:63]
	s_cselect_b64 s[48:49], -1, 0
	v_mfma_f32_16x16x32_bf16 v[56:59], v[100:103], v[104:107], v[56:59]
	v_mfma_f32_16x16x32_bf16 v[48:51], v[116:119], v[104:107], v[48:51]
	v_mfma_f32_16x16x32_bf16 v[44:47], v[52:55], v[104:107], v[44:47]
	v_mfma_f32_16x16x32_bf16 v[136:139], v[128:131], v[104:107], v[36:39]
	s_waitcnt lgkmcnt(0)
	v_mfma_f32_16x16x32_bf16 v[32:35], v[40:43], v[104:107], v[32:35]
	v_mfma_f32_16x16x32_bf16 v[104:107], v[52:55], v[108:111], v[8:11]
	s_nop 2
	v_add_u32_e32 v8, v64, v89
	v_mfma_f32_16x16x32_bf16 v[24:27], v[80:83], v[108:111], v[24:27]
	v_add3_u32 v9, s27, v89, v88
	v_lshl_or_b32 v64, s26, 7, v90
	s_sub_i32 s26, s26, 18
	v_mfma_f32_16x16x32_bf16 v[80:83], v[112:115], v[108:111], v[16:19]
	s_cmp_lt_u32 s26, 8
	s_cselect_b64 s[26:27], -1, 0
	s_or_b64 s[48:49], s[48:49], s[26:27]
	v_mfma_f32_16x16x32_bf16 v[112:115], v[124:127], v[108:111], v[4:7]
	s_mov_b64 s[26:27], -1
	s_andn2_b64 vcc, exec, s[48:49]
	s_nop 0
	ds_read_b128 v[4:7], v8 offset:16384
	v_mfma_f32_16x16x32_bf16 v[20:23], v[100:103], v[108:111], v[20:23]
	v_mfma_f32_16x16x32_bf16 v[100:103], v[116:119], v[108:111], v[12:15]
	v_mfma_f32_16x16x32_bf16 v[116:119], v[128:131], v[108:111], v[0:3]
	ds_read_b128 v[124:127], v8 offset:18432
	s_nop 1
	ds_read_b128 v[0:3], v9
	ds_read_b128 v[128:131], v9 offset:2048
	ds_read_b128 v[140:143], v8 offset:22528
	ds_read_b128 v[146:149], v8 offset:28672
	s_waitcnt lgkmcnt(3)
	v_mfma_f32_16x16x32_bf16 v[52:55], v[4:7], v[0:3], v[60:63]
	s_nop 2
	ds_read_b128 v[60:63], v8 offset:20480
	v_mfma_f32_16x16x32_bf16 v[108:111], v[40:43], v[108:111], v[28:31]
	s_waitcnt lgkmcnt(0)
	v_mfma_f32_16x16x32_bf16 v[36:39], v[60:63], v[0:3], v[120:123]
	s_nop 2
	ds_read_b128 v[120:123], v8 offset:24576
	v_mfma_f32_16x16x32_bf16 v[40:43], v[140:143], v[0:3], v[48:51]
	s_nop 2
	ds_read_b128 v[48:51], v8 offset:26624
	s_waitcnt lgkmcnt(0)
	v_mfma_f32_16x16x32_bf16 v[16:19], v[48:51], v[0:3], v[132:135]
	s_nop 2
	ds_read_b128 v[132:135], v8 offset:30720
	v_mfma_f32_16x16x32_bf16 v[56:59], v[124:127], v[0:3], v[56:59]
	v_mfma_f32_16x16x32_bf16 v[12:15], v[120:123], v[0:3], v[44:47]
	v_mfma_f32_16x16x32_bf16 v[8:11], v[146:149], v[0:3], v[136:139]
	s_waitcnt lgkmcnt(0)
	v_mfma_f32_16x16x32_bf16 v[0:3], v[132:135], v[0:3], v[32:35]
	v_mfma_f32_16x16x32_bf16 v[28:31], v[4:7], v[128:131], v[24:27]
	v_mfma_f32_16x16x32_bf16 v[20:23], v[124:127], v[128:131], v[20:23]
	v_mfma_f32_16x16x32_bf16 v[4:7], v[60:63], v[128:131], v[80:83]
	v_mfma_f32_16x16x32_bf16 v[24:27], v[140:143], v[128:131], v[100:103]
	s_nop 1
	v_lshl_add_u32 v80, s46, 7, v85
	v_mfma_f32_16x16x32_bf16 v[32:35], v[120:123], v[128:131], v[104:107]
	v_mfma_f32_16x16x32_bf16 v[44:47], v[48:51], v[128:131], v[112:115]
	v_mfma_f32_16x16x32_bf16 v[48:51], v[146:149], v[128:131], v[116:119]
	v_mfma_f32_16x16x32_bf16 v[60:63], v[132:135], v[128:131], v[108:111]
	s_cbranch_vccz .LBB0_240
	s_and_b32 s47, 0xffff, s45
	s_cmp_gt_u32 s47, 17
	s_cbranch_scc0 .LBB0_237
	s_cmp_eq_u32 s47, 26
	s_cselect_b64 s[26:27], -1, 0
	s_and_b64 s[48:49], s[10:11], s[26:27]
	s_and_saveexec_b64 s[26:27], s[48:49]
	s_cbranch_execz .LBB0_236
	global_load_dwordx4 v[100:103], v[72:73], off
	v_mad_i64_i32 v[82:83], s[48:49], v80, s28, v[70:71]
	v_or_b32_e32 v81, 16, v80
	s_waitcnt vmcnt(0)
	v_pk_add_f32 v[102:103], v[54:55], v[102:103]
	v_pk_add_f32 v[100:101], v[52:53], v[100:101]
	global_store_dwordx4 v[82:83], v[100:103], off
	global_load_dwordx4 v[100:103], v[72:73], off offset:16
	v_mad_i64_i32 v[82:83], s[48:49], v80, s28, v[74:75]
	s_waitcnt vmcnt(0)
	v_pk_add_f32 v[102:103], v[58:59], v[102:103]
	v_pk_add_f32 v[100:101], v[56:57], v[100:101]
	global_store_dwordx4 v[82:83], v[100:103], off
	global_load_dwordx4 v[100:103], v[72:73], off
	v_mad_i64_i32 v[82:83], s[48:49], v81, s28, v[70:71]
	s_waitcnt vmcnt(0)
	v_pk_add_f32 v[102:103], v[30:31], v[102:103]
	v_pk_add_f32 v[100:101], v[28:29], v[100:101]
	global_store_dwordx4 v[82:83], v[100:103], off
	global_load_dwordx4 v[100:103], v[72:73], off offset:16
	v_mad_i64_i32 v[82:83], s[48:49], v81, s28, v[74:75]
	s_waitcnt vmcnt(0)
	v_pk_add_f32 v[102:103], v[22:23], v[102:103]
	v_pk_add_f32 v[100:101], v[20:21], v[100:101]
	global_store_dwordx4 v[82:83], v[100:103], off

.LBB0_855:
	s_add_i32 s45, s43, 0x8000
	s_and_b32 s44, s45, 0x8000
	s_add_i32 s44, s44, 0
	v_add_u32_e32 v113, s44, v87
	v_lshl_add_u64 v[76:77], v[72:73], 0, s[34:35]
	v_readfirstlane_b32 s46, v113
	v_add_u32_e32 v114, 0x4000, v113
	v_lshl_add_u64 v[78:79], v[74:75], 0, s[34:35]
	v_lshl_add_u64 v[80:81], v[76:77], 0, s[14:15]
	v_add_u32_e32 v115, 0x1000, v113
	v_readfirstlane_b32 s47, v114
	s_mov_b32 m0, s46
	s_waitcnt vmcnt(0) lgkmcnt(0)
	s_barrier
	s_and_b32 s43, s43, 0x8000
	s_add_i32 s43, s43, 0
	v_add3_u32 v236, s43, v88, v89
	v_add3_u32 v237, s43, v89, v90
	v_add3_u32 v238, s43, v88, v91
	v_add3_u32 v239, s43, v90, v91
	ds_read_b128 v[180:183], v237
	ds_read_b128 v[172:175], v236 offset:16384
	ds_read_b128 v[176:179], v236 offset:18432
	ds_read_b128 v[184:187], v237 offset:2048
	ds_read_b128 v[188:191], v236 offset:20480
	ds_read_b128 v[192:195], v236 offset:22528
	ds_read_b128 v[122:125], v236 offset:24576
	ds_read_b128 v[126:129], v236 offset:26624
	ds_read_b128 v[130:133], v236 offset:28672
	ds_read_b128 v[134:137], v236 offset:30720
	v_lshl_add_u64 v[102:103], v[78:79], 0, s[16:17]
	v_add_u32_e32 v116, 0x5000, v113
	v_readfirstlane_b32 s48, v115
	global_load_lds_dwordx4 v[80:81], off
	s_mov_b32 m0, s47
	v_lshl_add_u64 v[104:105], v[76:77], 0, s[18:19]
	v_add_u32_e32 v117, 0x2000, v113
	v_readfirstlane_b32 s49, v116
	global_load_lds_dwordx4 v[102:103], off
	s_mov_b32 m0, s48
	v_lshl_add_u64 v[106:107], v[78:79], 0, s[20:21]
	v_add_u32_e32 v118, 0x6000, v113
	v_readfirstlane_b32 s50, v117
	global_load_lds_dwordx4 v[104:105], off
	s_mov_b32 m0, s49
	v_lshl_add_u64 v[108:109], v[76:77], 0, s[22:23]
	v_add_u32_e32 v119, 0x3000, v113
	v_readfirstlane_b32 s51, v118
	global_load_lds_dwordx4 v[106:107], off
	s_mov_b32 m0, s50
	v_lshl_add_u64 v[110:111], v[78:79], 0, s[24:25]
	v_add_u32_e32 v113, 0x7000, v113
	v_readfirstlane_b32 s52, v119
	global_load_lds_dwordx4 v[108:109], off
	s_mov_b32 m0, s51
	v_lshl_add_u64 v[76:77], v[76:77], 0, s[26:27]
	v_readfirstlane_b32 s53, v113
	global_load_lds_dwordx4 v[110:111], off
	s_mov_b32 m0, s52
	v_lshl_add_u64 v[78:79], v[78:79], 0, s[28:29]
	global_load_lds_dwordx4 v[76:77], off
	s_mov_b32 m0, s53
	global_load_lds_dwordx4 v[78:79], off
	ds_read_b128 v[204:207], v239
	ds_read_b128 v[196:199], v238 offset:16384
	ds_read_b128 v[200:203], v238 offset:18432
	ds_read_b128 v[208:211], v239 offset:2048
	ds_read_b128 v[212:215], v238 offset:20480
	ds_read_b128 v[216:219], v238 offset:22528
	ds_read_b128 v[220:223], v238 offset:24576
	ds_read_b128 v[224:227], v238 offset:26624
	ds_read_b128 v[228:231], v238 offset:28672
	ds_read_b128 v[232:235], v238 offset:30720
	s_add_u32 s34, s34, 0x80
	s_addc_u32 s35, s35, 0
	s_cmpk_eq_i32 s34, 0x780
	s_mov_b32 s43, s45
	s_waitcnt lgkmcnt(15)
	v_mfma_f32_16x16x32_bf16 v[60:63], v[172:175], v[180:183], v[60:63]
	v_mfma_f32_16x16x32_bf16 v[56:59], v[176:179], v[180:183], v[56:59]
	v_mfma_f32_16x16x32_bf16 v[24:27], v[172:175], v[184:187], v[24:27]
	v_mfma_f32_16x16x32_bf16 v[20:23], v[176:179], v[184:187], v[20:23]
	v_mfma_f32_16x16x32_bf16 v[52:55], v[188:191], v[180:183], v[52:55]
	v_mfma_f32_16x16x32_bf16 v[16:19], v[188:191], v[184:187], v[16:19]
	s_waitcnt lgkmcnt(14)
	v_mfma_f32_16x16x32_bf16 v[48:51], v[192:195], v[180:183], v[48:51]
	v_mfma_f32_16x16x32_bf16 v[12:15], v[192:195], v[184:187], v[12:15]
	s_waitcnt lgkmcnt(13)
	v_mfma_f32_16x16x32_bf16 v[44:47], v[122:125], v[180:183], v[44:47]
	v_mfma_f32_16x16x32_bf16 v[8:11], v[122:125], v[184:187], v[8:11]
	s_waitcnt lgkmcnt(12)
	v_mfma_f32_16x16x32_bf16 v[40:43], v[126:129], v[180:183], v[40:43]
	v_mfma_f32_16x16x32_bf16 v[4:7], v[126:129], v[184:187], v[4:7]
	s_waitcnt lgkmcnt(11)
	v_mfma_f32_16x16x32_bf16 v[32:35], v[130:133], v[180:183], v[32:35]
	v_mfma_f32_16x16x32_bf16 v[0:3], v[130:133], v[184:187], v[0:3]
	s_waitcnt lgkmcnt(10)
	v_mfma_f32_16x16x32_bf16 v[28:31], v[134:137], v[180:183], v[28:31]
	v_mfma_f32_16x16x32_bf16 v[36:39], v[134:137], v[184:187], v[36:39]
	s_waitcnt lgkmcnt(8)
	v_mfma_f32_16x16x32_bf16 v[60:63], v[196:199], v[204:207], v[60:63]
	s_waitcnt lgkmcnt(7)
	v_mfma_f32_16x16x32_bf16 v[56:59], v[200:203], v[204:207], v[56:59]
	s_waitcnt lgkmcnt(6)
	v_mfma_f32_16x16x32_bf16 v[24:27], v[196:199], v[208:211], v[24:27]
	v_mfma_f32_16x16x32_bf16 v[20:23], v[200:203], v[208:211], v[20:23]
	s_waitcnt lgkmcnt(5)
	v_mfma_f32_16x16x32_bf16 v[52:55], v[212:215], v[204:207], v[52:55]
	v_mfma_f32_16x16x32_bf16 v[16:19], v[212:215], v[208:211], v[16:19]
	s_waitcnt lgkmcnt(4)
	v_mfma_f32_16x16x32_bf16 v[48:51], v[216:219], v[204:207], v[48:51]
	v_mfma_f32_16x16x32_bf16 v[12:15], v[216:219], v[208:211], v[12:15]
	s_waitcnt lgkmcnt(3)
	v_mfma_f32_16x16x32_bf16 v[44:47], v[220:223], v[204:207], v[44:47]
	v_mfma_f32_16x16x32_bf16 v[8:11], v[220:223], v[208:211], v[8:11]
	s_waitcnt lgkmcnt(2)
	v_mfma_f32_16x16x32_bf16 v[40:43], v[224:227], v[204:207], v[40:43]
	v_mfma_f32_16x16x32_bf16 v[4:7], v[224:227], v[208:211], v[4:7]
	s_waitcnt lgkmcnt(1)
	v_mfma_f32_16x16x32_bf16 v[32:35], v[228:231], v[204:207], v[32:35]
	v_mfma_f32_16x16x32_bf16 v[0:3], v[228:231], v[208:211], v[0:3]
	s_waitcnt lgkmcnt(0)
	v_mfma_f32_16x16x32_bf16 v[28:31], v[232:235], v[204:207], v[28:31]
	v_mfma_f32_16x16x32_bf16 v[36:39], v[232:235], v[208:211], v[36:39]
	s_cbranch_scc0 .LBB0_855
	v_add_u32_e32 v80, s44, v88
	v_add_u32_e32 v81, v80, v89
	v_add3_u32 v106, s44, v89, v90
	s_waitcnt vmcnt(0)
	s_barrier
	ds_read_b128 v[72:75], v81 offset:16384
	ds_read_b128 v[76:79], v81 offset:18432
	ds_read_b128 v[102:105], v106
	ds_read_b128 v[106:109], v106 offset:2048
	ds_read_b128 v[110:113], v81 offset:20480
	ds_read_b128 v[114:117], v81 offset:22528
	ds_read_b128 v[118:121], v81 offset:24576
	ds_read_b128 v[122:125], v81 offset:26624
	ds_read_b128 v[126:129], v81 offset:28672
	ds_read_b128 v[130:133], v81 offset:30720
	v_add_u32_e32 v80, v80, v91
	s_waitcnt lgkmcnt(7)
	v_mfma_f32_16x16x32_bf16 v[60:63], v[72:75], v[102:105], v[60:63]
	s_lshl_b32 s42, s42, 7
	v_mfma_f32_16x16x32_bf16 v[56:59], v[76:79], v[102:105], v[56:59]
	s_waitcnt lgkmcnt(4)
	v_mfma_f32_16x16x32_bf16 v[48:51], v[114:117], v[102:105], v[48:51]
	s_waitcnt lgkmcnt(3)
	v_mfma_f32_16x16x32_bf16 v[44:47], v[118:121], v[102:105], v[44:47]
	s_waitcnt lgkmcnt(2)
	v_mfma_f32_16x16x32_bf16 v[40:43], v[122:125], v[102:105], v[40:43]
	s_waitcnt lgkmcnt(1)
	v_mfma_f32_16x16x32_bf16 v[32:35], v[126:129], v[102:105], v[32:35]
	s_waitcnt lgkmcnt(0)
	v_mfma_f32_16x16x32_bf16 v[28:31], v[130:133], v[102:105], v[28:31]
	v_mfma_f32_16x16x32_bf16 v[24:27], v[72:75], v[106:109], v[24:27]
	ds_read_b128 v[72:75], v80 offset:16384
	v_mfma_f32_16x16x32_bf16 v[52:55], v[110:113], v[102:105], v[52:55]
	v_mfma_f32_16x16x32_bf16 v[20:23], v[76:79], v[106:109], v[20:23]
	v_mfma_f32_16x16x32_bf16 v[16:19], v[110:113], v[106:109], v[16:19]
	v_mfma_f32_16x16x32_bf16 v[12:15], v[114:117], v[106:109], v[12:15]
	v_mfma_f32_16x16x32_bf16 v[8:11], v[118:121], v[106:109], v[8:11]
	v_mfma_f32_16x16x32_bf16 v[4:7], v[122:125], v[106:109], v[4:7]
	v_mfma_f32_16x16x32_bf16 v[0:3], v[126:129], v[106:109], v[0:3]
	v_mfma_f32_16x16x32_bf16 v[102:105], v[130:133], v[106:109], v[36:39]
	s_nop 2
	v_add3_u32 v36, s44, v91, v90
	ds_read_b128 v[76:79], v80 offset:18432
	ds_read_b128 v[106:109], v36
	ds_read_b128 v[110:113], v36 offset:2048
	ds_read_b128 v[130:133], v80 offset:28672
	ds_read_b128 v[134:137], v80 offset:30720
	ds_read_b128 v[114:117], v80 offset:20480
	ds_read_b128 v[118:121], v80 offset:22528
	ds_read_b128 v[122:125], v80 offset:24576
	ds_read_b128 v[126:129], v80 offset:26624
	s_waitcnt lgkmcnt(7)
	v_mfma_f32_16x16x32_bf16 v[60:63], v[72:75], v[106:109], v[60:63]
	v_readlane_b32 s44, v252, 5
	v_readlane_b32 s48, v252, 9
	v_readlane_b32 s49, v252, 10
	s_waitcnt lgkmcnt(5)
	v_mfma_f32_16x16x32_bf16 v[36:39], v[130:133], v[106:109], v[32:35]
	v_readlane_b32 s45, v252, 6
	v_readlane_b32 s46, v252, 7
	v_readlane_b32 s47, v252, 8
	s_waitcnt lgkmcnt(4)
	v_mfma_f32_16x16x32_bf16 v[32:35], v[134:137], v[106:109], v[28:31]
	v_readlane_b32 s50, v252, 11
	v_readlane_b32 s51, v252, 12
	v_readlane_b32 s52, v252, 13
	v_mfma_f32_16x16x32_bf16 v[28:31], v[72:75], v[110:113], v[24:27]
	v_add_u32_e32 v72, s42, v82
	v_mul_hi_i32 v73, v72, s36
	v_lshrrev_b32_e32 v74, 31, v73
	v_mfma_f32_16x16x32_bf16 v[24:27], v[76:79], v[110:113], v[20:23]
	v_readlane_b32 s53, v252, 14
	v_readlane_b32 s54, v252, 15
	v_readlane_b32 s55, v252, 16
	s_waitcnt lgkmcnt(3)
	v_mfma_f32_16x16x32_bf16 v[20:23], v[114:117], v[110:113], v[16:19]
	v_readlane_b32 s56, v252, 17
	v_readlane_b32 s57, v252, 18
	v_readlane_b32 s58, v252, 19
	s_waitcnt lgkmcnt(2)
	v_mfma_f32_16x16x32_bf16 v[16:19], v[118:121], v[110:113], v[12:15]
	v_readlane_b32 s59, v252, 20
	s_waitcnt lgkmcnt(1)
	v_mfma_f32_16x16x32_bf16 v[12:15], v[122:125], v[110:113], v[8:11]
	s_waitcnt lgkmcnt(0)
	v_mfma_f32_16x16x32_bf16 v[8:11], v[126:129], v[110:113], v[4:7]
	s_nop 2
	v_ashrrev_i32_e32 v4, 11, v73
	v_mfma_f32_16x16x32_bf16 v[56:59], v[76:79], v[106:109], v[56:59]
	v_add_u32_e32 v73, v4, v74
	v_mad_i32_i24 v75, v73, s37, v72
	v_lshlrev_b32_e32 v78, 13, v73
	v_mfma_f32_16x16x32_bf16 v[52:55], v[114:117], v[106:109], v[52:55]
	v_cmp_lt_i32_e32 vcc, s38, v75
	v_mov_b64_e32 v[76:77], s[48:49]
	v_add3_u32 v74, v78, v75, s39
	v_mfma_f32_16x16x32_bf16 v[48:51], v[118:121], v[106:109], v[48:51]
	v_mfma_f32_16x16x32_bf16 v[44:47], v[122:125], v[106:109], v[44:47]
	v_mfma_f32_16x16x32_bf16 v[40:43], v[126:129], v[106:109], v[40:43]
	v_mfma_f32_16x16x32_bf16 v[0:3], v[130:133], v[110:113], v[0:3]
	v_mfma_f32_16x16x32_bf16 v[4:7], v[134:137], v[110:113], v[102:105]
	s_and_saveexec_b64 s[34:35], vcc
	s_xor_b64 s[34:35], exec, s[34:35]
	s_cbranch_execz .LBB0_858
	v_readlane_b32 s44, v252, 5
	v_readlane_b32 s45, v252, 6
	v_add3_u32 v72, v78, v75, s39
	v_readlane_b32 s46, v252, 7
	v_readlane_b32 s47, v252, 8
	v_readlane_b32 s48, v252, 9
	v_readlane_b32 s49, v252, 10
	v_readlane_b32 s50, v252, 11
	v_readlane_b32 s51, v252, 12
	v_readlane_b32 s52, v252, 13
	v_readlane_b32 s53, v252, 14
	v_readlane_b32 s54, v252, 15
	v_readlane_b32 s55, v252, 16
	v_readlane_b32 s56, v252, 17
	v_readlane_b32 s57, v252, 18
	v_readlane_b32 s58, v252, 19
	v_readlane_b32 s59, v252, 20
	v_mov_b64_e32 v[76:77], s[44:45]
	s_or_saveexec_b64 s[34:35], s[34:35]
	v_lshl_add_u32 v102, v73, 8, v75
	s_xor_b64 exec, exec, s[34:35]
	s_branch .LBB0_859

.LBB0_1006:
	s_add_i32 s37, s35, 0x8000
	s_and_b32 s36, s37, 0x8000
	s_add_i32 s36, s36, 0
	v_add_u32_e32 v111, s36, v78
	v_lshl_add_u64 v[94:95], v[74:75], 0, s[26:27]
	v_readfirstlane_b32 s38, v111
	v_add_u32_e32 v112, 0x4000, v111
	v_lshl_add_u64 v[96:97], v[76:77], 0, s[26:27]
	v_lshl_add_u64 v[98:99], v[94:95], 0, s[10:11]
	v_add_u32_e32 v113, 0x1000, v111
	v_readfirstlane_b32 s39, v112
	s_mov_b32 m0, s38
	s_waitcnt vmcnt(0) lgkmcnt(0)
	s_barrier
	s_and_b32 s35, s35, 0x8000
	s_add_i32 s35, s35, 0
	v_add3_u32 v143, s35, v80, v81
	v_add3_u32 v145, s35, v81, v82
	v_add3_u32 v230, s35, v80, v83
	v_add3_u32 v231, s35, v82, v83
	ds_read_b128 v[174:177], v145
	ds_read_b128 v[166:169], v143 offset:16384
	ds_read_b128 v[170:173], v143 offset:18432
	ds_read_b128 v[178:181], v145 offset:2048
	ds_read_b128 v[182:185], v143 offset:20480
	ds_read_b128 v[186:189], v143 offset:22528
	ds_read_b128 v[118:121], v143 offset:24576
	ds_read_b128 v[122:125], v143 offset:26624
	ds_read_b128 v[126:129], v143 offset:28672
	ds_read_b128 v[130:133], v143 offset:30720
	v_lshl_add_u64 v[100:101], v[96:97], 0, s[12:13]
	v_add_u32_e32 v114, 0x5000, v111
	v_readfirstlane_b32 s40, v113
	global_load_lds_dwordx4 v[98:99], off
	s_mov_b32 m0, s39
	v_lshl_add_u64 v[102:103], v[94:95], 0, s[14:15]
	v_add_u32_e32 v115, 0x2000, v111
	v_readfirstlane_b32 s41, v114
	global_load_lds_dwordx4 v[100:101], off
	s_mov_b32 m0, s40
	v_lshl_add_u64 v[104:105], v[96:97], 0, s[16:17]
	v_add_u32_e32 v116, 0x6000, v111
	v_readfirstlane_b32 s42, v115
	global_load_lds_dwordx4 v[102:103], off
	s_mov_b32 m0, s41
	v_lshl_add_u64 v[106:107], v[94:95], 0, s[18:19]
	v_add_u32_e32 v117, 0x3000, v111
	v_readfirstlane_b32 s43, v116
	global_load_lds_dwordx4 v[104:105], off
	s_mov_b32 m0, s42
	v_lshl_add_u64 v[108:109], v[96:97], 0, s[20:21]
	v_add_u32_e32 v111, 0x7000, v111
	v_readfirstlane_b32 s44, v117
	global_load_lds_dwordx4 v[106:107], off
	s_mov_b32 m0, s43
	v_lshl_add_u64 v[94:95], v[94:95], 0, s[22:23]
	v_readfirstlane_b32 s45, v111
	global_load_lds_dwordx4 v[108:109], off
	s_mov_b32 m0, s44
	v_lshl_add_u64 v[96:97], v[96:97], 0, s[24:25]
	global_load_lds_dwordx4 v[94:95], off
	s_mov_b32 m0, s45
	global_load_lds_dwordx4 v[96:97], off
	ds_read_b128 v[198:201], v231
	ds_read_b128 v[190:193], v230 offset:16384
	ds_read_b128 v[194:197], v230 offset:18432
	ds_read_b128 v[202:205], v231 offset:2048
	ds_read_b128 v[206:209], v230 offset:20480
	ds_read_b128 v[210:213], v230 offset:22528
	ds_read_b128 v[214:217], v230 offset:24576
	ds_read_b128 v[218:221], v230 offset:26624
	ds_read_b128 v[222:225], v230 offset:28672
	ds_read_b128 v[226:229], v230 offset:30720
	s_add_u32 s26, s26, 0x80
	s_addc_u32 s27, s27, 0
	s_cmpk_eq_i32 s26, 0x780
	s_mov_b32 s35, s37
	s_waitcnt lgkmcnt(15)
	v_mfma_f32_16x16x32_bf16 v[60:63], v[166:169], v[174:177], v[60:63]
	v_mfma_f32_16x16x32_bf16 v[56:59], v[170:173], v[174:177], v[56:59]
	v_mfma_f32_16x16x32_bf16 v[28:31], v[166:169], v[178:181], v[28:31]
	v_mfma_f32_16x16x32_bf16 v[24:27], v[170:173], v[178:181], v[24:27]
	v_mfma_f32_16x16x32_bf16 v[52:55], v[182:185], v[174:177], v[52:55]
	v_mfma_f32_16x16x32_bf16 v[16:19], v[182:185], v[178:181], v[16:19]
	s_waitcnt lgkmcnt(14)
	v_mfma_f32_16x16x32_bf16 v[48:51], v[186:189], v[174:177], v[48:51]
	v_mfma_f32_16x16x32_bf16 v[12:15], v[186:189], v[178:181], v[12:15]
	s_waitcnt lgkmcnt(13)
	v_mfma_f32_16x16x32_bf16 v[44:47], v[118:121], v[174:177], v[44:47]
	v_mfma_f32_16x16x32_bf16 v[8:11], v[118:121], v[178:181], v[8:11]
	s_waitcnt lgkmcnt(12)
	v_mfma_f32_16x16x32_bf16 v[40:43], v[122:125], v[174:177], v[40:43]
	v_mfma_f32_16x16x32_bf16 v[4:7], v[122:125], v[178:181], v[4:7]
	s_waitcnt lgkmcnt(11)
	v_mfma_f32_16x16x32_bf16 v[36:39], v[126:129], v[174:177], v[36:39]
	v_mfma_f32_16x16x32_bf16 v[0:3], v[126:129], v[178:181], v[0:3]
	s_waitcnt lgkmcnt(10)
	v_mfma_f32_16x16x32_bf16 v[32:35], v[130:133], v[174:177], v[32:35]
	v_mfma_f32_16x16x32_bf16 v[20:23], v[130:133], v[178:181], v[20:23]
	s_waitcnt lgkmcnt(8)
	v_mfma_f32_16x16x32_bf16 v[60:63], v[190:193], v[198:201], v[60:63]
	s_waitcnt lgkmcnt(7)
	v_mfma_f32_16x16x32_bf16 v[56:59], v[194:197], v[198:201], v[56:59]
	s_waitcnt lgkmcnt(6)
	v_mfma_f32_16x16x32_bf16 v[28:31], v[190:193], v[202:205], v[28:31]
	v_mfma_f32_16x16x32_bf16 v[24:27], v[194:197], v[202:205], v[24:27]
	s_waitcnt lgkmcnt(5)
	v_mfma_f32_16x16x32_bf16 v[52:55], v[206:209], v[198:201], v[52:55]
	v_mfma_f32_16x16x32_bf16 v[16:19], v[206:209], v[202:205], v[16:19]
	s_waitcnt lgkmcnt(4)
	v_mfma_f32_16x16x32_bf16 v[48:51], v[210:213], v[198:201], v[48:51]
	v_mfma_f32_16x16x32_bf16 v[12:15], v[210:213], v[202:205], v[12:15]
	s_waitcnt lgkmcnt(3)
	v_mfma_f32_16x16x32_bf16 v[44:47], v[214:217], v[198:201], v[44:47]
	v_mfma_f32_16x16x32_bf16 v[8:11], v[214:217], v[202:205], v[8:11]
	s_waitcnt lgkmcnt(2)
	v_mfma_f32_16x16x32_bf16 v[40:43], v[218:221], v[198:201], v[40:43]
	v_mfma_f32_16x16x32_bf16 v[4:7], v[218:221], v[202:205], v[4:7]
	s_waitcnt lgkmcnt(1)
	v_mfma_f32_16x16x32_bf16 v[36:39], v[222:225], v[198:201], v[36:39]
	v_mfma_f32_16x16x32_bf16 v[0:3], v[222:225], v[202:205], v[0:3]
	s_waitcnt lgkmcnt(0)
	v_mfma_f32_16x16x32_bf16 v[32:35], v[226:229], v[198:201], v[32:35]
	v_mfma_f32_16x16x32_bf16 v[20:23], v[226:229], v[202:205], v[20:23]
	s_cbranch_scc0 .LBB0_1006
	v_add_u32_e32 v138, s36, v80
	v_add_u32_e32 v126, v138, v81
	s_waitcnt vmcnt(0)
	s_barrier
	ds_read_b128 v[74:77], v126 offset:16384
	v_add3_u32 v102, s36, v81, v82
	ds_read_b128 v[94:97], v102
	ds_read_b128 v[98:101], v126 offset:18432
	ds_read_b128 v[102:105], v102 offset:2048
	ds_read_b128 v[106:109], v126 offset:20480
	ds_read_b128 v[110:113], v126 offset:22528
	ds_read_b128 v[114:117], v126 offset:24576
	ds_read_b128 v[118:121], v126 offset:26624
	v_add3_u32 v134, s36, v83, v82
	v_add_u32_e32 v142, v138, v83
	ds_read_b128 v[122:125], v126 offset:28672
	ds_read_b128 v[126:129], v126 offset:30720
	ds_read_b128 v[130:133], v134
	ds_read_b128 v[134:137], v134 offset:2048
	ds_read_b128 v[138:141], v142 offset:16384
	ds_read_b128 v[146:149], v142 offset:18432
	s_waitcnt lgkmcnt(11)
	v_mfma_f32_16x16x32_bf16 v[56:59], v[98:101], v[94:97], v[56:59]
	s_lshl_b32 s36, s34, 7
	s_lshl_b32 s26, s33, 7
	s_ashr_i32 s27, s26, 31
	v_mfma_f32_16x16x32_bf16 v[60:63], v[74:77], v[94:97], v[60:63]
	s_lshl_b64 s[26:27], s[26:27], 1
	s_add_i32 s31, s31, s28
	s_cmpk_gt_i32 s31, 0x107f
	s_waitcnt lgkmcnt(0)
	v_mfma_f32_16x16x32_bf16 v[56:59], v[146:149], v[130:133], v[56:59]
	v_mfma_f32_16x16x32_bf16 v[48:51], v[110:113], v[94:97], v[48:51]
	v_mfma_f32_16x16x32_bf16 v[52:55], v[106:109], v[94:97], v[52:55]
	s_nop 5
	v_max_f32_e32 v56, v56, v56
	v_max_f32_e32 v57, v57, v57
	v_max_f32_e32 v56, 0, v56
	v_mfma_f32_16x16x32_bf16 v[44:47], v[114:117], v[94:97], v[44:47]
	v_max_f32_e32 v57, 0, v57
	v_max_f32_e32 v59, v59, v59
	v_max_f32_e32 v59, 0, v59
	v_mfma_f32_16x16x32_bf16 v[40:43], v[118:121], v[94:97], v[40:43]
	v_mfma_f32_16x16x32_bf16 v[36:39], v[122:125], v[94:97], v[36:39]
	v_mfma_f32_16x16x32_bf16 v[32:35], v[126:129], v[94:97], v[32:35]
	ds_read_b128 v[94:97], v142 offset:20480
	ds_read_b128 v[150:153], v142 offset:22528
	ds_read_b128 v[154:157], v142 offset:24576
	ds_read_b128 v[158:161], v142 offset:26624
	v_mfma_f32_16x16x32_bf16 v[60:63], v[138:141], v[130:133], v[60:63]
	s_waitcnt lgkmcnt(2)
	v_mfma_f32_16x16x32_bf16 v[48:51], v[150:153], v[130:133], v[48:51]
	v_mfma_f32_16x16x32_bf16 v[16:19], v[106:109], v[102:105], v[16:19]
	v_mul_f32_e64 v106, v56, v56
	v_mul_f32_e64 v107, v57, v57
	v_max_f32_e32 v57, v58, v58
	s_nop 1
	v_max_f32_e32 v60, v60, v60
	v_mfma_f32_16x16x32_bf16 v[24:27], v[98:101], v[102:105], v[24:27]
	v_add_u32_e32 v100, s36, v79
	v_mov_b64_e32 v[98:99], s[0:1]
	v_max_f32_e32 v61, v61, v61
	v_max_f32_e32 v56, v62, v62
	v_max_f32_e32 v58, 0, v57
	v_max_f32_e32 v57, v63, v63
	v_mad_i64_i32 v[100:101], s[34:35], v100, s30, v[98:99]
	v_max_f32_e32 v60, 0, v60
	v_max_f32_e32 v61, 0, v61
	v_max_f32_e32 v56, 0, v56
	v_max_f32_e32 v57, 0, v57
	v_mfma_f32_16x16x32_bf16 v[52:55], v[94:97], v[130:133], v[52:55]
	v_lshl_add_u64 v[100:101], v[100:101], 0, s[26:27]
	v_pk_mul_f32 v[60:61], v[60:61], v[60:61]
	v_pk_mul_f32 v[62:63], v[56:57], v[56:57]
	v_mfma_f32_16x16x32_bf16 v[28:31], v[74:77], v[102:105], v[28:31]
	v_max_f32_e32 v48, v48, v48
	v_max_f32_e32 v49, v49, v49
	ds_read_b128 v[74:77], v142 offset:28672
	ds_read_b128 v[162:165], v142 offset:30720
	v_mfma_f32_16x16x32_bf16 v[12:15], v[110:113], v[102:105], v[12:15]
	v_lshl_add_u64 v[100:101], v[100:101], 0, v[64:65]
	v_cvt_pk_bf16_f32 v56, v60, v61
	v_cvt_pk_bf16_f32 v57, v62, v63
	v_mfma_f32_16x16x32_bf16 v[8:11], v[114:117], v[102:105], v[8:11]
	v_max_f32_e32 v48, 0, v48
	v_max_f32_e32 v49, 0, v49
	v_max_f32_e32 v52, v52, v52
	v_mfma_f32_16x16x32_bf16 v[4:7], v[118:121], v[102:105], v[4:7]
	v_max_f32_e32 v53, v53, v53
	v_max_f32_e32 v51, v51, v51
	v_max_f32_e32 v52, 0, v52
	v_mfma_f32_16x16x32_bf16 v[0:3], v[122:125], v[102:105], v[0:3]
	v_max_f32_e32 v53, 0, v53
	v_max_f32_e32 v51, 0, v51
	v_pk_mul_f32 v[52:53], v[52:53], v[52:53]
	v_mfma_f32_16x16x32_bf16 v[20:23], v[126:129], v[102:105], v[20:23]
	v_mul_f32_e64 v102, v58, v58
	v_mul_f32_e64 v103, v59, v59
	v_cvt_pk_bf16_f32 v58, v106, v107
	v_cvt_pk_bf16_f32 v59, v102, v103
	s_waitcnt lgkmcnt(2)
	v_mfma_f32_16x16x32_bf16 v[40:43], v[158:161], v[130:133], v[40:43]
	global_store_dwordx4 v[100:101], v[56:59], off
	s_nop 1
	v_pk_mul_f32 v[56:57], v[48:49], v[48:49]
	v_max_f32_e32 v49, v50, v50
	v_max_f32_e32 v48, v54, v54
	v_max_f32_e32 v50, 0, v49
	v_max_f32_e32 v49, v55, v55
	v_mfma_f32_16x16x32_bf16 v[44:47], v[154:157], v[130:133], v[44:47]
	v_max_f32_e32 v48, 0, v48
	v_max_f32_e32 v49, 0, v49
	v_pk_mul_f32 v[54:55], v[48:49], v[48:49]
	v_pk_mul_f32 v[58:59], v[50:51], v[50:51]
	v_max_f32_e32 v40, v40, v40
	v_max_f32_e32 v41, v41, v41
	s_waitcnt lgkmcnt(0)
	v_mfma_f32_16x16x32_bf16 v[32:35], v[162:165], v[130:133], v[32:35]
	v_cvt_pk_bf16_f32 v48, v52, v53
	v_cvt_pk_bf16_f32 v49, v54, v55
	v_cvt_pk_bf16_f32 v50, v56, v57
	v_cvt_pk_bf16_f32 v51, v58, v59
	v_max_f32_e32 v40, 0, v40
	v_max_f32_e32 v41, 0, v41
	global_store_dwordx4 v[100:101], v[48:51], off offset:64
	v_max_f32_e32 v44, v44, v44
	v_max_f32_e32 v45, v45, v45
	v_pk_mul_f32 v[48:49], v[40:41], v[40:41]
	v_max_f32_e32 v41, v42, v42
	v_max_f32_e32 v40, v46, v46
	v_max_f32_e32 v42, 0, v41
	v_max_f32_e32 v41, v47, v47
	v_max_f32_e32 v43, v43, v43
	v_mfma_f32_16x16x32_bf16 v[36:39], v[74:77], v[130:133], v[36:39]
	v_max_f32_e32 v44, 0, v44
	v_max_f32_e32 v45, 0, v45
	v_max_f32_e32 v40, 0, v40
	v_max_f32_e32 v41, 0, v41
	v_max_f32_e32 v43, 0, v43
	v_pk_mul_f32 v[44:45], v[44:45], v[44:45]
	v_pk_mul_f32 v[46:47], v[40:41], v[40:41]
	v_pk_mul_f32 v[50:51], v[42:43], v[42:43]
	v_max_f32_e32 v32, v32, v32
	v_max_f32_e32 v33, v33, v33
	v_mfma_f32_16x16x32_bf16 v[24:27], v[146:149], v[134:137], v[24:27]
	v_cvt_pk_bf16_f32 v40, v44, v45
	v_cvt_pk_bf16_f32 v41, v46, v47
	v_cvt_pk_bf16_f32 v42, v48, v49
	v_cvt_pk_bf16_f32 v43, v50, v51
	v_max_f32_e32 v32, 0, v32
	v_max_f32_e32 v33, 0, v33
	global_store_dwordx4 v[100:101], v[40:43], off offset:128
	v_max_f32_e32 v36, v36, v36
	v_max_f32_e32 v37, v37, v37
	v_pk_mul_f32 v[40:41], v[32:33], v[32:33]
	v_max_f32_e32 v33, v34, v34
	v_max_f32_e32 v32, v38, v38
	v_max_f32_e32 v34, 0, v33
	v_max_f32_e32 v33, v39, v39
	v_max_f32_e32 v35, v35, v35
	v_mfma_f32_16x16x32_bf16 v[28:31], v[138:141], v[134:137], v[28:31]
	v_max_f32_e32 v36, 0, v36
	v_max_f32_e32 v37, 0, v37
	v_max_f32_e32 v32, 0, v32
	v_max_f32_e32 v33, 0, v33
	v_max_f32_e32 v35, 0, v35
	v_pk_mul_f32 v[36:37], v[36:37], v[36:37]
	v_pk_mul_f32 v[38:39], v[32:33], v[32:33]
	v_pk_mul_f32 v[42:43], v[34:35], v[34:35]
	v_max_f32_e32 v24, v24, v24
	v_max_f32_e32 v25, v25, v25
	v_mfma_f32_16x16x32_bf16 v[12:15], v[150:153], v[134:137], v[12:15]
	v_cvt_pk_bf16_f32 v32, v36, v37
	v_cvt_pk_bf16_f32 v33, v38, v39
	v_cvt_pk_bf16_f32 v34, v40, v41
	v_cvt_pk_bf16_f32 v35, v42, v43
	v_max_f32_e32 v24, 0, v24
	v_max_f32_e32 v25, 0, v25
	global_store_dwordx4 v[100:101], v[32:35], off offset:192
	v_max_f32_e32 v28, v28, v28
	v_max_f32_e32 v29, v29, v29
	v_pk_mul_f32 v[34:35], v[24:25], v[24:25]
	v_max_f32_e32 v25, v26, v26
	v_add_u32_e32 v32, s36, v84
	v_max_f32_e32 v24, v30, v30
	v_max_f32_e32 v26, 0, v25
	v_max_f32_e32 v25, v31, v31
	v_max_f32_e32 v27, v27, v27
	v_mfma_f32_16x16x32_bf16 v[16:19], v[94:97], v[134:137], v[16:19]
	v_mad_i64_i32 v[32:33], s[34:35], v32, s30, v[98:99]
	v_max_f32_e32 v28, 0, v28
	v_max_f32_e32 v29, 0, v29
	v_max_f32_e32 v24, 0, v24
	v_max_f32_e32 v25, 0, v25
	v_max_f32_e32 v27, 0, v27
	v_lshl_add_u64 v[32:33], v[32:33], 0, s[26:27]
	v_pk_mul_f32 v[28:29], v[28:29], v[28:29]
	v_pk_mul_f32 v[30:31], v[24:25], v[24:25]
	v_pk_mul_f32 v[36:37], v[26:27], v[26:27]
	v_max_f32_e32 v12, v12, v12
	v_max_f32_e32 v13, v13, v13
	v_mfma_f32_16x16x32_bf16 v[4:7], v[158:161], v[134:137], v[4:7]
	v_lshl_add_u64 v[32:33], v[32:33], 0, v[64:65]
	v_cvt_pk_bf16_f32 v24, v28, v29
	v_cvt_pk_bf16_f32 v25, v30, v31
	v_cvt_pk_bf16_f32 v26, v34, v35
	v_cvt_pk_bf16_f32 v27, v36, v37
	v_max_f32_e32 v12, 0, v12
	v_max_f32_e32 v13, 0, v13
	global_store_dwordx4 v[32:33], v[24:27], off
	v_max_f32_e32 v16, v16, v16
	v_max_f32_e32 v17, v17, v17
	v_pk_mul_f32 v[24:25], v[12:13], v[12:13]
	v_max_f32_e32 v13, v14, v14
	v_max_f32_e32 v12, v18, v18
	v_max_f32_e32 v14, 0, v13
	v_max_f32_e32 v13, v19, v19
	v_max_f32_e32 v15, v15, v15
	v_mfma_f32_16x16x32_bf16 v[8:11], v[154:157], v[134:137], v[8:11]
	v_max_f32_e32 v16, 0, v16
	v_max_f32_e32 v17, 0, v17
	v_max_f32_e32 v12, 0, v12
	v_max_f32_e32 v13, 0, v13
	v_max_f32_e32 v15, 0, v15
	v_pk_mul_f32 v[16:17], v[16:17], v[16:17]
	v_pk_mul_f32 v[18:19], v[12:13], v[12:13]
	v_pk_mul_f32 v[26:27], v[14:15], v[14:15]
	v_max_f32_e32 v4, v4, v4
	v_max_f32_e32 v5, v5, v5
	v_cvt_pk_bf16_f32 v12, v16, v17
	v_cvt_pk_bf16_f32 v13, v18, v19
	v_cvt_pk_bf16_f32 v14, v24, v25
	v_cvt_pk_bf16_f32 v15, v26, v27
	v_max_f32_e32 v4, 0, v4
	v_max_f32_e32 v5, 0, v5
	global_store_dwordx4 v[32:33], v[12:15], off offset:64
	v_mfma_f32_16x16x32_bf16 v[0:3], v[74:77], v[134:137], v[0:3]
	v_max_f32_e32 v8, v8, v8
	v_pk_mul_f32 v[12:13], v[4:5], v[4:5]
	v_max_f32_e32 v5, v6, v6
	v_mfma_f32_16x16x32_bf16 v[20:23], v[162:165], v[134:137], v[20:23]
	v_max_f32_e32 v9, v9, v9
	v_max_f32_e32 v4, v10, v10
	v_max_f32_e32 v6, 0, v5
	v_max_f32_e32 v5, v11, v11
	v_max_f32_e32 v7, v7, v7
	v_max_f32_e32 v8, 0, v8
	v_max_f32_e32 v9, 0, v9
	v_max_f32_e32 v4, 0, v4
	v_max_f32_e32 v5, 0, v5
	v_max_f32_e32 v7, 0, v7
	v_pk_mul_f32 v[8:9], v[8:9], v[8:9]
	v_pk_mul_f32 v[10:11], v[4:5], v[4:5]
	v_pk_mul_f32 v[14:15], v[6:7], v[6:7]
	v_cvt_pk_bf16_f32 v4, v8, v9
	v_cvt_pk_bf16_f32 v5, v10, v11
	v_cvt_pk_bf16_f32 v6, v12, v13
	v_cvt_pk_bf16_f32 v7, v14, v15
	global_store_dwordx4 v[32:33], v[4:7], off offset:128
	v_max_f32_e32 v0, v0, v0
	v_max_f32_e32 v1, v1, v1
	v_max_f32_e32 v4, v20, v20
	v_max_f32_e32 v5, v21, v21
	v_max_f32_e32 v2, v2, v2
	v_max_f32_e32 v6, v22, v22
	v_max_f32_e32 v3, v3, v3
	v_max_f32_e32 v7, v23, v23
	v_max_f32_e32 v0, 0, v0
	v_max_f32_e32 v4, 0, v4
	v_max_f32_e32 v1, 0, v1
	v_max_f32_e32 v5, 0, v5
	v_max_f32_e32 v2, 0, v2
	v_max_f32_e32 v6, 0, v6
	v_max_f32_e32 v3, 0, v3
	v_max_f32_e32 v7, 0, v7
	v_pk_mul_f32 v[0:1], v[0:1], v[0:1]
	v_pk_mul_f32 v[4:5], v[4:5], v[4:5]
	v_pk_mul_f32 v[2:3], v[2:3], v[2:3]
	v_pk_mul_f32 v[6:7], v[6:7], v[6:7]
	v_cvt_pk_bf16_f32 v0, v0, v1
	v_cvt_pk_bf16_f32 v1, v2, v3
	v_cvt_pk_bf16_f32 v2, v4, v5
	v_cvt_pk_bf16_f32 v3, v6, v7
	global_store_dwordx4 v[32:33], v[0:3], off offset:192
	s_cbranch_scc0 .LBB0_1005

.LBB0_1071:
	s_add_i32 s45, s43, 0x8000
	s_and_b32 s44, s45, 0x8000
	s_add_i32 s44, s44, 0
	v_add_u32_e32 v113, s44, v88
	v_lshl_add_u64 v[76:77], v[72:73], 0, s[34:35]
	v_readfirstlane_b32 s46, v113
	v_add_u32_e32 v114, 0x4000, v113
	v_lshl_add_u64 v[78:79], v[74:75], 0, s[34:35]
	v_lshl_add_u64 v[80:81], v[76:77], 0, s[14:15]
	v_add_u32_e32 v115, 0x1000, v113
	v_readfirstlane_b32 s47, v114
	s_mov_b32 m0, s46
	s_waitcnt vmcnt(0) lgkmcnt(0)
	s_barrier
	s_and_b32 s43, s43, 0x8000
	s_add_i32 s43, s43, 0
	v_add3_u32 v169, s43, v84, v89
	v_add3_u32 v234, s43, v89, v90
	v_add3_u32 v235, s43, v84, v91
	v_add3_u32 v236, s43, v90, v91
	ds_read_b128 v[178:181], v234
	ds_read_b128 v[170:173], v169 offset:16384
	ds_read_b128 v[174:177], v169 offset:18432
	ds_read_b128 v[182:185], v234 offset:2048
	ds_read_b128 v[186:189], v169 offset:20480
	ds_read_b128 v[190:193], v169 offset:22528
	ds_read_b128 v[122:125], v169 offset:24576
	ds_read_b128 v[126:129], v169 offset:26624
	ds_read_b128 v[130:133], v169 offset:28672
	ds_read_b128 v[134:137], v169 offset:30720
	v_lshl_add_u64 v[102:103], v[78:79], 0, s[16:17]
	v_add_u32_e32 v116, 0x5000, v113
	v_readfirstlane_b32 s48, v115
	global_load_lds_dwordx4 v[80:81], off
	s_mov_b32 m0, s47
	v_lshl_add_u64 v[104:105], v[76:77], 0, s[18:19]
	v_add_u32_e32 v117, 0x2000, v113
	v_readfirstlane_b32 s49, v116
	global_load_lds_dwordx4 v[102:103], off
	s_mov_b32 m0, s48
	v_lshl_add_u64 v[106:107], v[78:79], 0, s[20:21]
	v_add_u32_e32 v118, 0x6000, v113
	v_readfirstlane_b32 s50, v117
	global_load_lds_dwordx4 v[104:105], off
	s_mov_b32 m0, s49
	v_lshl_add_u64 v[108:109], v[76:77], 0, s[22:23]
	v_add_u32_e32 v119, 0x3000, v113
	v_readfirstlane_b32 s51, v118
	global_load_lds_dwordx4 v[106:107], off
	s_mov_b32 m0, s50
	v_lshl_add_u64 v[110:111], v[78:79], 0, s[24:25]
	v_add_u32_e32 v113, 0x7000, v113
	v_readfirstlane_b32 s52, v119
	global_load_lds_dwordx4 v[108:109], off
	s_mov_b32 m0, s51
	v_lshl_add_u64 v[76:77], v[76:77], 0, s[26:27]
	v_readfirstlane_b32 s53, v113
	global_load_lds_dwordx4 v[110:111], off
	s_mov_b32 m0, s52
	v_lshl_add_u64 v[78:79], v[78:79], 0, s[28:29]
	global_load_lds_dwordx4 v[76:77], off
	s_mov_b32 m0, s53
	global_load_lds_dwordx4 v[78:79], off
	ds_read_b128 v[202:205], v236
	ds_read_b128 v[194:197], v235 offset:16384
	ds_read_b128 v[198:201], v235 offset:18432
	ds_read_b128 v[206:209], v236 offset:2048
	ds_read_b128 v[210:213], v235 offset:20480
	ds_read_b128 v[214:217], v235 offset:22528
	ds_read_b128 v[218:221], v235 offset:24576
	ds_read_b128 v[222:225], v235 offset:26624
	ds_read_b128 v[226:229], v235 offset:28672
	ds_read_b128 v[230:233], v235 offset:30720
	s_add_u32 s34, s34, 0x80
	s_addc_u32 s35, s35, 0
	s_cmpk_eq_i32 s34, 0x1f80
	s_mov_b32 s43, s45
	s_waitcnt lgkmcnt(15)
	v_mfma_f32_16x16x32_bf16 v[60:63], v[170:173], v[178:181], v[60:63]
	v_mfma_f32_16x16x32_bf16 v[56:59], v[174:177], v[178:181], v[56:59]
	v_mfma_f32_16x16x32_bf16 v[24:27], v[170:173], v[182:185], v[24:27]
	v_mfma_f32_16x16x32_bf16 v[20:23], v[174:177], v[182:185], v[20:23]
	v_mfma_f32_16x16x32_bf16 v[52:55], v[186:189], v[178:181], v[52:55]
	v_mfma_f32_16x16x32_bf16 v[16:19], v[186:189], v[182:185], v[16:19]
	s_waitcnt lgkmcnt(14)
	v_mfma_f32_16x16x32_bf16 v[48:51], v[190:193], v[178:181], v[48:51]
	v_mfma_f32_16x16x32_bf16 v[12:15], v[190:193], v[182:185], v[12:15]
	s_waitcnt lgkmcnt(13)
	v_mfma_f32_16x16x32_bf16 v[44:47], v[122:125], v[178:181], v[44:47]
	v_mfma_f32_16x16x32_bf16 v[8:11], v[122:125], v[182:185], v[8:11]
	s_waitcnt lgkmcnt(12)
	v_mfma_f32_16x16x32_bf16 v[40:43], v[126:129], v[178:181], v[40:43]
	v_mfma_f32_16x16x32_bf16 v[4:7], v[126:129], v[182:185], v[4:7]
	s_waitcnt lgkmcnt(11)
	v_mfma_f32_16x16x32_bf16 v[32:35], v[130:133], v[178:181], v[32:35]
	v_mfma_f32_16x16x32_bf16 v[0:3], v[130:133], v[182:185], v[0:3]
	s_waitcnt lgkmcnt(10)
	v_mfma_f32_16x16x32_bf16 v[28:31], v[134:137], v[178:181], v[28:31]
	v_mfma_f32_16x16x32_bf16 v[36:39], v[134:137], v[182:185], v[36:39]
	s_waitcnt lgkmcnt(8)
	v_mfma_f32_16x16x32_bf16 v[60:63], v[194:197], v[202:205], v[60:63]
	s_waitcnt lgkmcnt(7)
	v_mfma_f32_16x16x32_bf16 v[56:59], v[198:201], v[202:205], v[56:59]
	s_waitcnt lgkmcnt(6)
	v_mfma_f32_16x16x32_bf16 v[24:27], v[194:197], v[206:209], v[24:27]
	v_mfma_f32_16x16x32_bf16 v[20:23], v[198:201], v[206:209], v[20:23]
	s_waitcnt lgkmcnt(5)
	v_mfma_f32_16x16x32_bf16 v[52:55], v[210:213], v[202:205], v[52:55]
	v_mfma_f32_16x16x32_bf16 v[16:19], v[210:213], v[206:209], v[16:19]
	s_waitcnt lgkmcnt(4)
	v_mfma_f32_16x16x32_bf16 v[48:51], v[214:217], v[202:205], v[48:51]
	v_mfma_f32_16x16x32_bf16 v[12:15], v[214:217], v[206:209], v[12:15]
	s_waitcnt lgkmcnt(3)
	v_mfma_f32_16x16x32_bf16 v[44:47], v[218:221], v[202:205], v[44:47]
	v_mfma_f32_16x16x32_bf16 v[8:11], v[218:221], v[206:209], v[8:11]
	s_waitcnt lgkmcnt(2)
	v_mfma_f32_16x16x32_bf16 v[40:43], v[222:225], v[202:205], v[40:43]
	v_mfma_f32_16x16x32_bf16 v[4:7], v[222:225], v[206:209], v[4:7]
	s_waitcnt lgkmcnt(1)
	v_mfma_f32_16x16x32_bf16 v[32:35], v[226:229], v[202:205], v[32:35]
	v_mfma_f32_16x16x32_bf16 v[0:3], v[226:229], v[206:209], v[0:3]
	s_waitcnt lgkmcnt(0)
	v_mfma_f32_16x16x32_bf16 v[28:31], v[230:233], v[202:205], v[28:31]
	v_mfma_f32_16x16x32_bf16 v[36:39], v[230:233], v[206:209], v[36:39]
	s_cbranch_scc0 .LBB0_1071
	v_add_u32_e32 v80, s44, v84
	v_add_u32_e32 v81, v80, v89
	v_add3_u32 v106, s44, v89, v90
	s_waitcnt vmcnt(0)
	s_barrier
	ds_read_b128 v[72:75], v81 offset:16384
	ds_read_b128 v[76:79], v81 offset:18432
	ds_read_b128 v[102:105], v106
	ds_read_b128 v[106:109], v106 offset:2048
	ds_read_b128 v[110:113], v81 offset:20480
	ds_read_b128 v[114:117], v81 offset:22528
	ds_read_b128 v[118:121], v81 offset:24576
	ds_read_b128 v[122:125], v81 offset:26624
	ds_read_b128 v[126:129], v81 offset:28672
	ds_read_b128 v[130:133], v81 offset:30720
	v_add_u32_e32 v80, v80, v91
	s_waitcnt lgkmcnt(7)
	v_mfma_f32_16x16x32_bf16 v[60:63], v[72:75], v[102:105], v[60:63]
	s_lshl_b32 s42, s42, 7
	v_mfma_f32_16x16x32_bf16 v[56:59], v[76:79], v[102:105], v[56:59]
	s_waitcnt lgkmcnt(4)
	v_mfma_f32_16x16x32_bf16 v[48:51], v[114:117], v[102:105], v[48:51]
	s_waitcnt lgkmcnt(3)
	v_mfma_f32_16x16x32_bf16 v[44:47], v[118:121], v[102:105], v[44:47]
	s_waitcnt lgkmcnt(2)
	v_mfma_f32_16x16x32_bf16 v[40:43], v[122:125], v[102:105], v[40:43]
	s_waitcnt lgkmcnt(1)
	v_mfma_f32_16x16x32_bf16 v[32:35], v[126:129], v[102:105], v[32:35]
	s_waitcnt lgkmcnt(0)
	v_mfma_f32_16x16x32_bf16 v[28:31], v[130:133], v[102:105], v[28:31]
	v_mfma_f32_16x16x32_bf16 v[24:27], v[72:75], v[106:109], v[24:27]
	ds_read_b128 v[72:75], v80 offset:16384
	v_mfma_f32_16x16x32_bf16 v[52:55], v[110:113], v[102:105], v[52:55]
	v_mfma_f32_16x16x32_bf16 v[20:23], v[76:79], v[106:109], v[20:23]
	v_mfma_f32_16x16x32_bf16 v[16:19], v[110:113], v[106:109], v[16:19]
	v_mfma_f32_16x16x32_bf16 v[12:15], v[114:117], v[106:109], v[12:15]
	v_mfma_f32_16x16x32_bf16 v[8:11], v[118:121], v[106:109], v[8:11]
	v_mfma_f32_16x16x32_bf16 v[4:7], v[122:125], v[106:109], v[4:7]
	v_mfma_f32_16x16x32_bf16 v[0:3], v[126:129], v[106:109], v[0:3]
	v_mfma_f32_16x16x32_bf16 v[102:105], v[130:133], v[106:109], v[36:39]
	s_nop 2
	v_add3_u32 v36, s44, v91, v90
	ds_read_b128 v[76:79], v80 offset:18432
	ds_read_b128 v[106:109], v36
	ds_read_b128 v[110:113], v36 offset:2048
	ds_read_b128 v[130:133], v80 offset:28672
	ds_read_b128 v[134:137], v80 offset:30720
	ds_read_b128 v[114:117], v80 offset:20480
	ds_read_b128 v[118:121], v80 offset:22528
	ds_read_b128 v[122:125], v80 offset:24576
	ds_read_b128 v[126:129], v80 offset:26624
	s_waitcnt lgkmcnt(7)
	v_mfma_f32_16x16x32_bf16 v[60:63], v[72:75], v[106:109], v[60:63]
	s_waitcnt lgkmcnt(5)
	v_mfma_f32_16x16x32_bf16 v[36:39], v[130:133], v[106:109], v[32:35]
	s_waitcnt lgkmcnt(4)
	v_mfma_f32_16x16x32_bf16 v[32:35], v[134:137], v[106:109], v[28:31]
	v_mfma_f32_16x16x32_bf16 v[28:31], v[72:75], v[110:113], v[24:27]
	v_add_u32_e32 v72, s42, v85
	v_mul_hi_i32 v73, v72, s36
	v_mfma_f32_16x16x32_bf16 v[24:27], v[76:79], v[110:113], v[20:23]
	s_waitcnt lgkmcnt(3)
	v_mfma_f32_16x16x32_bf16 v[20:23], v[114:117], v[110:113], v[16:19]
	s_waitcnt lgkmcnt(2)
	v_mfma_f32_16x16x32_bf16 v[16:19], v[118:121], v[110:113], v[12:15]
	s_waitcnt lgkmcnt(1)
	v_mfma_f32_16x16x32_bf16 v[12:15], v[122:125], v[110:113], v[8:11]
	s_waitcnt lgkmcnt(0)
	v_mfma_f32_16x16x32_bf16 v[8:11], v[126:129], v[110:113], v[4:7]
	s_nop 2
	v_lshrrev_b32_e32 v4, 31, v73
	v_ashrrev_i32_e32 v5, 11, v73
	v_mfma_f32_16x16x32_bf16 v[56:59], v[76:79], v[106:109], v[56:59]
	v_add_u32_e32 v73, v5, v4
	v_mad_i32_i24 v78, v73, s37, v72
	v_lshlrev_b32_e32 v75, 13, v73
	v_mfma_f32_16x16x32_bf16 v[52:55], v[114:117], v[106:109], v[52:55]
	v_cmp_lt_i32_e32 vcc, s38, v78
	v_add3_u32 v74, v75, v78, s39
	v_mfma_f32_16x16x32_bf16 v[48:51], v[118:121], v[106:109], v[48:51]
	v_mfma_f32_16x16x32_bf16 v[44:47], v[122:125], v[106:109], v[44:47]
	v_mfma_f32_16x16x32_bf16 v[40:43], v[126:129], v[106:109], v[40:43]
	v_mfma_f32_16x16x32_bf16 v[4:7], v[130:133], v[110:113], v[0:3]
	v_mfma_f32_16x16x32_bf16 v[0:3], v[134:137], v[110:113], v[102:105]
	s_and_saveexec_b64 s[34:35], vcc
	s_xor_b64 s[34:35], exec, s[34:35]
	v_add3_u32 v72, v75, v78, s39
	s_or_saveexec_b64 s[34:35], s[34:35]
	v_mov_b64_e32 v[76:77], s[92:93]
	v_lshl_add_u32 v75, v73, 8, v78
	s_xor_b64 exec, exec, s[34:35]
	v_lshl_add_u32 v72, v73, 8, v78
	v_mov_b64_e32 v[76:77], s[6:7]
	s_or_b64 exec, exec, s[34:35]
	s_and_saveexec_b64 s[34:35], vcc
	s_xor_b64 s[34:35], exec, s[34:35]
	s_cbranch_execz .LBB0_1078
	v_mul_hi_i32_i24_e32 v79, 0x6000, v73
	v_mul_i32_i24_e32 v78, 0x6000, v73
	s_or_saveexec_b64 s[34:35], s[34:35]
	v_mov_b64_e32 v[80:81], s[92:93]
	s_xor_b64 exec, exec, s[34:35]
	s_cbranch_execnz .LBB0_1079
	s_branch .LBB0_1080

.LBB0_1091:
	s_add_i32 s48, s47, 0x8000
	s_and_b32 s8, s47, 0x8000
	s_and_b32 s47, s48, 0x8000
	s_add_i32 s49, s8, 0
	s_add_i32 s8, s47, 0
	v_add_u32_e32 v112, s8, v88
	v_lshl_add_u64 v[68:69], v[66:67], 0, s[36:37]
	v_readfirstlane_b32 s47, v112
	v_add_u32_e32 v113, 0x4000, v112
	v_lshl_add_u64 v[70:71], v[64:65], 0, s[36:37]
	v_lshl_add_u64 v[100:101], v[68:69], 0, s[16:17]
	v_add_u32_e32 v114, 0x1000, v112
	v_readfirstlane_b32 s50, v113
	s_mov_b32 m0, s47
	s_waitcnt vmcnt(0) lgkmcnt(0)
	s_barrier
	v_add3_u32 v169, s49, v84, v87
	v_add3_u32 v234, s49, v87, v89
	v_add3_u32 v235, s49, v84, v90
	v_add3_u32 v236, s49, v89, v90
	ds_read_b128 v[178:181], v234
	ds_read_b128 v[170:173], v169 offset:16384
	ds_read_b128 v[174:177], v169 offset:18432
	ds_read_b128 v[182:185], v234 offset:2048
	ds_read_b128 v[186:189], v169 offset:20480
	ds_read_b128 v[190:193], v169 offset:22528
	ds_read_b128 v[120:123], v169 offset:24576
	ds_read_b128 v[124:127], v169 offset:26624
	ds_read_b128 v[128:131], v169 offset:28672
	ds_read_b128 v[132:135], v169 offset:30720
	v_lshl_add_u64 v[102:103], v[70:71], 0, s[18:19]
	v_add_u32_e32 v115, 0x5000, v112
	v_readfirstlane_b32 s51, v114
	global_load_lds_dwordx4 v[100:101], off
	s_mov_b32 m0, s50
	v_lshl_add_u64 v[104:105], v[68:69], 0, s[20:21]
	v_add_u32_e32 v116, 0x2000, v112
	v_readfirstlane_b32 s52, v115
	global_load_lds_dwordx4 v[102:103], off
	s_mov_b32 m0, s51
	v_lshl_add_u64 v[106:107], v[70:71], 0, s[22:23]
	v_add_u32_e32 v117, 0x6000, v112
	v_readfirstlane_b32 s53, v116
	global_load_lds_dwordx4 v[104:105], off
	s_mov_b32 m0, s52
	v_lshl_add_u64 v[108:109], v[68:69], 0, s[24:25]
	v_add_u32_e32 v118, 0x3000, v112
	v_readfirstlane_b32 s54, v117
	global_load_lds_dwordx4 v[106:107], off
	s_mov_b32 m0, s53
	v_lshl_add_u64 v[110:111], v[70:71], 0, s[26:27]
	v_add_u32_e32 v112, 0x7000, v112
	v_readfirstlane_b32 s55, v118
	global_load_lds_dwordx4 v[108:109], off
	s_mov_b32 m0, s54
	v_lshl_add_u64 v[68:69], v[68:69], 0, s[28:29]
	v_readfirstlane_b32 s56, v112
	global_load_lds_dwordx4 v[110:111], off
	s_mov_b32 m0, s55
	v_lshl_add_u64 v[70:71], v[70:71], 0, s[30:31]
	global_load_lds_dwordx4 v[68:69], off
	s_mov_b32 m0, s56
	global_load_lds_dwordx4 v[70:71], off
	ds_read_b128 v[202:205], v236
	ds_read_b128 v[194:197], v235 offset:16384
	ds_read_b128 v[198:201], v235 offset:18432
	ds_read_b128 v[206:209], v236 offset:2048
	ds_read_b128 v[210:213], v235 offset:20480
	ds_read_b128 v[214:217], v235 offset:22528
	ds_read_b128 v[218:221], v235 offset:24576
	ds_read_b128 v[222:225], v235 offset:26624
	ds_read_b128 v[226:229], v235 offset:28672
	ds_read_b128 v[230:233], v235 offset:30720
	s_add_u32 s36, s36, 0x80
	s_addc_u32 s37, s37, 0
	s_cmpk_eq_i32 s36, 0x780
	s_mov_b32 s47, s48
	s_waitcnt lgkmcnt(15)
	v_mfma_f32_16x16x32_bf16 v[60:63], v[170:173], v[178:181], v[60:63]
	v_mfma_f32_16x16x32_bf16 v[56:59], v[174:177], v[178:181], v[56:59]
	v_mfma_f32_16x16x32_bf16 v[28:31], v[170:173], v[182:185], v[28:31]
	v_mfma_f32_16x16x32_bf16 v[24:27], v[174:177], v[182:185], v[24:27]
	v_mfma_f32_16x16x32_bf16 v[52:55], v[186:189], v[178:181], v[52:55]
	v_mfma_f32_16x16x32_bf16 v[16:19], v[186:189], v[182:185], v[16:19]
	s_waitcnt lgkmcnt(14)
	v_mfma_f32_16x16x32_bf16 v[48:51], v[190:193], v[178:181], v[48:51]
	v_mfma_f32_16x16x32_bf16 v[12:15], v[190:193], v[182:185], v[12:15]
	s_waitcnt lgkmcnt(13)
	v_mfma_f32_16x16x32_bf16 v[44:47], v[120:123], v[178:181], v[44:47]
	v_mfma_f32_16x16x32_bf16 v[8:11], v[120:123], v[182:185], v[8:11]
	s_waitcnt lgkmcnt(12)
	v_mfma_f32_16x16x32_bf16 v[40:43], v[124:127], v[178:181], v[40:43]
	v_mfma_f32_16x16x32_bf16 v[4:7], v[124:127], v[182:185], v[4:7]
	s_waitcnt lgkmcnt(11)
	v_mfma_f32_16x16x32_bf16 v[36:39], v[128:131], v[178:181], v[36:39]
	v_mfma_f32_16x16x32_bf16 v[0:3], v[128:131], v[182:185], v[0:3]
	s_waitcnt lgkmcnt(10)
	v_mfma_f32_16x16x32_bf16 v[32:35], v[132:135], v[178:181], v[32:35]
	v_mfma_f32_16x16x32_bf16 v[20:23], v[132:135], v[182:185], v[20:23]
	s_waitcnt lgkmcnt(8)
	v_mfma_f32_16x16x32_bf16 v[60:63], v[194:197], v[202:205], v[60:63]
	s_waitcnt lgkmcnt(7)
	v_mfma_f32_16x16x32_bf16 v[56:59], v[198:201], v[202:205], v[56:59]
	s_waitcnt lgkmcnt(6)
	v_mfma_f32_16x16x32_bf16 v[28:31], v[194:197], v[206:209], v[28:31]
	v_mfma_f32_16x16x32_bf16 v[24:27], v[198:201], v[206:209], v[24:27]
	s_waitcnt lgkmcnt(5)
	v_mfma_f32_16x16x32_bf16 v[52:55], v[210:213], v[202:205], v[52:55]
	v_mfma_f32_16x16x32_bf16 v[16:19], v[210:213], v[206:209], v[16:19]
	s_waitcnt lgkmcnt(4)
	v_mfma_f32_16x16x32_bf16 v[48:51], v[214:217], v[202:205], v[48:51]
	v_mfma_f32_16x16x32_bf16 v[12:15], v[214:217], v[206:209], v[12:15]
	s_waitcnt lgkmcnt(3)
	v_mfma_f32_16x16x32_bf16 v[44:47], v[218:221], v[202:205], v[44:47]
	v_mfma_f32_16x16x32_bf16 v[8:11], v[218:221], v[206:209], v[8:11]
	s_waitcnt lgkmcnt(2)
	v_mfma_f32_16x16x32_bf16 v[40:43], v[222:225], v[202:205], v[40:43]
	v_mfma_f32_16x16x32_bf16 v[4:7], v[222:225], v[206:209], v[4:7]
	s_waitcnt lgkmcnt(1)
	v_mfma_f32_16x16x32_bf16 v[36:39], v[226:229], v[202:205], v[36:39]
	v_mfma_f32_16x16x32_bf16 v[0:3], v[226:229], v[206:209], v[0:3]
	s_waitcnt lgkmcnt(0)
	v_mfma_f32_16x16x32_bf16 v[32:35], v[230:233], v[202:205], v[32:35]
	v_mfma_f32_16x16x32_bf16 v[20:23], v[230:233], v[206:209], v[20:23]
	s_cbranch_scc0 .LBB0_1091
	v_lshl_add_u32 v99, s46, 7, v85
	v_mul_hi_i32 v64, v99, s39
	v_lshrrev_b32_e32 v65, 31, v64
	v_ashrrev_i32_e32 v64, 11, v64
	v_add_u32_e32 v64, v64, v65
	v_mad_i32_i24 v65, v64, s40, v99
	v_cmp_lt_i32_e32 vcc, s41, v65
	v_lshl_or_b32 v72, s45, 9, v86
	s_waitcnt vmcnt(0)
	v_cndmask_b32_e32 v64, 2, v64, vcc
	v_mul_hi_i32_i24_e32 v65, 0x6000, v64
	v_mul_i32_i24_e32 v64, 0x6000, v64
	v_lshl_add_u64 v[64:65], s[94:95], 0, v[64:65]
	v_lshl_add_u64 v[150:151], v[64:65], 0, s[34:35]
	v_lshl_add_u64 v[64:65], v[150:151], 0, v[72:73]
	s_barrier
	global_load_dwordx4 v[100:103], v[64:65], off
	v_add3_u32 v64, s8, v87, v89
	v_add_u32_e32 v68, s8, v84
	ds_read_b128 v[104:107], v64
	ds_read_b128 v[108:111], v64 offset:2048
	v_add3_u32 v65, s8, v90, v89
	v_add_u32_e32 v145, v68, v87
	ds_read_b128 v[112:115], v65
	ds_read_b128 v[64:67], v65 offset:2048
	v_add_u32_e32 v168, v68, v90
	ds_read_b128 v[116:119], v145 offset:16384
	ds_read_b128 v[120:123], v145 offset:18432
	ds_read_b128 v[124:127], v168 offset:16384
	ds_read_b128 v[68:71], v168 offset:18432
	v_mul_hi_i32 v128, v99, s38
	s_waitcnt lgkmcnt(3)
	v_mfma_f32_16x16x32_bf16 v[60:63], v[116:119], v[104:107], v[60:63]
	v_lshrrev_b32_e32 v129, 31, v128
	v_lshrrev_b32_e32 v128, 11, v128
	v_add_u32_e32 v128, v128, v129
	v_lshl_add_u32 v128, v128, 13, v99
	s_lshl_b32 s8, s44, 9
	v_ashrrev_i32_e32 v129, 31, v128
	s_waitcnt lgkmcnt(1)
	v_mfma_f32_16x16x32_bf16 v[60:63], v[124:127], v[112:115], v[60:63]
	v_lshl_add_u64 v[128:129], v[128:129], 0, s[8:9]
	v_lshlrev_b64 v[128:129], 12, v[128:129]
	v_lshl_add_u64 v[128:129], s[6:7], 0, v[128:129]
	v_mov_b32_e32 v153, v73
	v_or_b32_e32 v152, 16, v72
	v_lshl_add_u64 v[154:155], v[128:129], 0, v[72:73]
	v_lshl_add_u64 v[128:129], v[150:151], 0, v[152:153]
	v_mfma_f32_16x16x32_bf16 v[56:59], v[120:123], v[104:107], v[56:59]
	v_mov_b32_e32 v157, v73
	v_or_b32_e32 v156, 0x80, v72
	v_mov_b32_e32 v159, v73
	s_waitcnt lgkmcnt(0)
	v_mfma_f32_16x16x32_bf16 v[56:59], v[68:71], v[112:115], v[56:59]
	v_or_b32_e32 v158, 0x90, v72
	v_lshl_add_u64 v[136:137], v[150:151], 0, v[158:159]
	v_mov_b32_e32 v161, v73
	v_or_b32_e32 v160, 0x100, v72
	v_mov_b32_e32 v163, v73
	v_or_b32_e32 v162, 0x110, v72
	v_lshl_add_u64 v[146:147], v[150:151], 0, v[162:163]
	v_mov_b32_e32 v165, v73
	v_or_b32_e32 v164, 0x180, v72
	v_lshl_add_u64 v[166:167], v[150:151], 0, v[164:165]
	v_mfma_f32_16x16x32_bf16 v[28:31], v[116:119], v[108:111], v[28:31]
	v_or_b32_e32 v99, 16, v99
	s_add_i32 s43, s43, s33
	s_add_i32 s42, s42, s33
	v_mfma_f32_16x16x32_bf16 v[28:31], v[124:127], v[64:67], v[28:31]
	s_cmpk_gt_i32 s43, 0x7f
	s_waitcnt vmcnt(0)
	v_pk_mul_f32 v[62:63], v[62:63], v[102:103]
	v_pk_mul_f32 v[60:61], v[60:61], v[100:101]
	global_store_dwordx4 v[154:155], v[60:63], off
	global_load_dwordx4 v[60:63], v[128:129], off
	v_lshl_add_u64 v[100:101], v[150:151], 0, v[156:157]
	v_mfma_f32_16x16x32_bf16 v[24:27], v[120:123], v[108:111], v[24:27]
	s_waitcnt vmcnt(0)
	v_pk_mul_f32 v[58:59], v[58:59], v[62:63]
	v_pk_mul_f32 v[56:57], v[56:57], v[60:61]
	global_store_dwordx4 v[154:155], v[56:59], off offset:16
	global_load_dwordx4 v[56:59], v[100:101], off
	ds_read_b128 v[60:63], v145 offset:20480
	ds_read_b128 v[100:103], v168 offset:20480
	s_waitcnt lgkmcnt(1)
	v_mfma_f32_16x16x32_bf16 v[52:55], v[60:63], v[104:107], v[52:55]
	ds_read_b128 v[128:131], v145 offset:22528
	ds_read_b128 v[132:135], v168 offset:22528
	s_waitcnt lgkmcnt(2)
	v_mfma_f32_16x16x32_bf16 v[52:55], v[100:103], v[112:115], v[52:55]
	s_waitcnt lgkmcnt(1)
	v_mfma_f32_16x16x32_bf16 v[48:51], v[128:131], v[104:107], v[48:51]
	s_waitcnt vmcnt(0)
	s_nop 4
	v_pk_mul_f32 v[54:55], v[54:55], v[58:59]
	v_pk_mul_f32 v[52:53], v[52:53], v[56:57]
	global_store_dwordx4 v[154:155], v[52:55], off offset:128
	global_load_dwordx4 v[52:55], v[136:137], off
	s_waitcnt lgkmcnt(0)
	v_mfma_f32_16x16x32_bf16 v[48:51], v[132:135], v[112:115], v[48:51]
	v_lshl_add_u64 v[56:57], v[150:151], 0, v[160:161]
	v_mfma_f32_16x16x32_bf16 v[24:27], v[68:71], v[64:67], v[24:27]
	v_mfma_f32_16x16x32_bf16 v[16:19], v[60:63], v[108:111], v[16:19]
	s_waitcnt vmcnt(0)
	s_nop 3
	v_pk_mul_f32 v[50:51], v[50:51], v[54:55]
	v_pk_mul_f32 v[48:49], v[48:49], v[52:53]
	global_store_dwordx4 v[154:155], v[48:51], off offset:144
	global_load_dwordx4 v[48:51], v[56:57], off
	ds_read_b128 v[52:55], v145 offset:24576
	ds_read_b128 v[56:59], v168 offset:24576
	s_waitcnt lgkmcnt(1)
	v_mfma_f32_16x16x32_bf16 v[44:47], v[52:55], v[104:107], v[44:47]
	ds_read_b128 v[136:139], v145 offset:26624
	ds_read_b128 v[140:143], v168 offset:26624
	s_waitcnt lgkmcnt(2)
	v_mfma_f32_16x16x32_bf16 v[44:47], v[56:59], v[112:115], v[44:47]
	s_waitcnt lgkmcnt(1)
	v_mfma_f32_16x16x32_bf16 v[40:43], v[136:139], v[104:107], v[40:43]
	s_waitcnt vmcnt(0)
	s_nop 4
	v_pk_mul_f32 v[46:47], v[46:47], v[50:51]
	v_pk_mul_f32 v[44:45], v[44:45], v[48:49]
	global_store_dwordx4 v[154:155], v[44:47], off offset:256
	global_load_dwordx4 v[44:47], v[146:147], off
	s_waitcnt lgkmcnt(0)
	v_mfma_f32_16x16x32_bf16 v[40:43], v[140:143], v[112:115], v[40:43]
	ds_read_b128 v[48:51], v145 offset:28672
	ds_read_b128 v[146:149], v145 offset:30720
	s_waitcnt lgkmcnt(1)
	v_mfma_f32_16x16x32_bf16 v[36:39], v[48:51], v[104:107], v[36:39]
	s_waitcnt vmcnt(0)
	s_nop 2
	v_pk_mul_f32 v[42:43], v[42:43], v[46:47]
	v_pk_mul_f32 v[40:41], v[40:41], v[44:45]
	global_store_dwordx4 v[154:155], v[40:43], off offset:272
	global_load_dwordx4 v[40:43], v[166:167], off
	ds_read_b128 v[44:47], v168 offset:28672
	s_waitcnt lgkmcnt(1)
	v_mfma_f32_16x16x32_bf16 v[32:35], v[146:149], v[104:107], v[32:35]
	ds_read_b128 v[104:107], v168 offset:30720
	v_mov_b32_e32 v167, v73
	v_or_b32_e32 v166, 0x190, v72
	s_waitcnt lgkmcnt(1)
	v_mfma_f32_16x16x32_bf16 v[36:39], v[44:47], v[112:115], v[36:39]
	v_lshl_add_u64 v[116:117], v[150:151], 0, v[166:167]
	s_waitcnt vmcnt(0)
	s_nop 5
	v_pk_mul_f32 v[38:39], v[38:39], v[42:43]
	v_pk_mul_f32 v[36:37], v[36:37], v[40:41]
	global_store_dwordx4 v[154:155], v[36:39], off offset:384
	global_load_dwordx4 v[36:39], v[116:117], off
	v_mul_hi_i32 v40, v99, s39
	v_lshrrev_b32_e32 v41, 31, v40
	v_ashrrev_i32_e32 v40, 11, v40
	v_add_u32_e32 v40, v40, v41
	v_mad_i32_i24 v41, v40, s40, v99
	v_cmp_lt_i32_e32 vcc, s41, v41
	s_waitcnt lgkmcnt(0)
	v_mfma_f32_16x16x32_bf16 v[32:35], v[104:107], v[112:115], v[32:35]
	v_cndmask_b32_e32 v40, 2, v40, vcc
	v_mul_hi_i32_i24_e32 v41, 0x6000, v40
	v_mul_i32_i24_e32 v40, 0x6000, v40
	v_lshl_add_u64 v[40:41], s[94:95], 0, v[40:41]
	v_lshl_add_u64 v[40:41], v[40:41], 0, s[34:35]
	v_lshl_add_u64 v[42:43], v[40:41], 0, v[72:73]
	v_mfma_f32_16x16x32_bf16 v[16:19], v[100:103], v[64:67], v[16:19]
	s_waitcnt vmcnt(0)
	v_pk_mul_f32 v[34:35], v[34:35], v[38:39]
	v_pk_mul_f32 v[32:33], v[32:33], v[36:37]
	global_store_dwordx4 v[154:155], v[32:35], off offset:400
	global_load_dwordx4 v[32:35], v[42:43], off
	v_mul_hi_i32 v36, v99, s38
	v_lshrrev_b32_e32 v37, 31, v36
	v_lshrrev_b32_e32 v36, 11, v36
	v_add_u32_e32 v36, v36, v37
	v_lshl_add_u32 v36, v36, 13, v99
	v_ashrrev_i32_e32 v37, 31, v36
	v_lshl_add_u64 v[36:37], v[36:37], 0, s[8:9]
	v_lshlrev_b64 v[36:37], 12, v[36:37]
	v_lshl_add_u64 v[36:37], s[6:7], 0, v[36:37]
	v_lshl_add_u64 v[36:37], v[36:37], 0, v[72:73]
	v_lshl_add_u64 v[38:39], v[40:41], 0, v[152:153]
	v_mfma_f32_16x16x32_bf16 v[12:15], v[128:131], v[108:111], v[12:15]
	s_waitcnt vmcnt(0)
	v_pk_mul_f32 v[30:31], v[30:31], v[34:35]
	v_pk_mul_f32 v[28:29], v[28:29], v[32:33]
	global_store_dwordx4 v[36:37], v[28:31], off
	global_load_dwordx4 v[28:31], v[38:39], off
	v_lshl_add_u64 v[32:33], v[40:41], 0, v[156:157]
	v_mfma_f32_16x16x32_bf16 v[12:15], v[132:135], v[64:67], v[12:15]
	s_waitcnt vmcnt(0)
	v_pk_mul_f32 v[26:27], v[26:27], v[30:31]
	v_pk_mul_f32 v[24:25], v[24:25], v[28:29]
	global_store_dwordx4 v[36:37], v[24:27], off offset:16
	global_load_dwordx4 v[24:27], v[32:33], off
	v_lshl_add_u64 v[28:29], v[40:41], 0, v[158:159]
	v_mfma_f32_16x16x32_bf16 v[8:11], v[52:55], v[108:111], v[8:11]
	s_waitcnt vmcnt(0)
	v_pk_mul_f32 v[18:19], v[18:19], v[26:27]
	v_pk_mul_f32 v[16:17], v[16:17], v[24:25]
	global_store_dwordx4 v[36:37], v[16:19], off offset:128
	global_load_dwordx4 v[16:19], v[28:29], off
	v_lshl_add_u64 v[24:25], v[40:41], 0, v[160:161]
	v_mfma_f32_16x16x32_bf16 v[8:11], v[56:59], v[64:67], v[8:11]
	s_waitcnt vmcnt(0)
	v_pk_mul_f32 v[14:15], v[14:15], v[18:19]
	v_pk_mul_f32 v[12:13], v[12:13], v[16:17]
	global_store_dwordx4 v[36:37], v[12:15], off offset:144
	global_load_dwordx4 v[12:15], v[24:25], off
	v_lshl_add_u64 v[16:17], v[40:41], 0, v[162:163]
	v_mfma_f32_16x16x32_bf16 v[4:7], v[136:139], v[108:111], v[4:7]
	s_waitcnt vmcnt(0)
	v_pk_mul_f32 v[10:11], v[10:11], v[14:15]
	v_pk_mul_f32 v[8:9], v[8:9], v[12:13]
	global_store_dwordx4 v[36:37], v[8:11], off offset:256
	global_load_dwordx4 v[8:11], v[16:17], off
	v_mfma_f32_16x16x32_bf16 v[4:7], v[140:143], v[64:67], v[4:7]
	v_lshl_add_u64 v[12:13], v[40:41], 0, v[164:165]
	v_mfma_f32_16x16x32_bf16 v[0:3], v[48:51], v[108:111], v[0:3]
	v_mfma_f32_16x16x32_bf16 v[0:3], v[44:47], v[64:67], v[0:3]
	s_waitcnt vmcnt(0)
	s_nop 3
	v_pk_mul_f32 v[6:7], v[6:7], v[10:11]
	v_pk_mul_f32 v[4:5], v[4:5], v[8:9]
	global_store_dwordx4 v[36:37], v[4:7], off offset:272
	global_load_dwordx4 v[4:7], v[12:13], off
	v_lshl_add_u64 v[8:9], v[40:41], 0, v[166:167]
	v_mfma_f32_16x16x32_bf16 v[20:23], v[146:149], v[108:111], v[20:23]
	s_waitcnt vmcnt(0)
	v_pk_mul_f32 v[2:3], v[2:3], v[6:7]
	v_pk_mul_f32 v[0:1], v[0:1], v[4:5]
	global_store_dwordx4 v[36:37], v[0:3], off offset:384
	global_load_dwordx4 v[0:3], v[8:9], off
	v_mfma_f32_16x16x32_bf16 v[4:7], v[104:107], v[64:67], v[20:23]
	s_waitcnt vmcnt(0)
	s_nop 6
	v_pk_mul_f32 v[2:3], v[6:7], v[2:3]
	v_pk_mul_f32 v[0:1], v[4:5], v[0:1]
	global_store_dwordx4 v[36:37], v[0:3], off offset:400
	s_cbranch_scc0 .LBB0_1090

.LBB0_1217:
	s_add_i32 s41, s3, 0x8000
	s_and_b32 s40, s41, 0x8000
	s_add_i32 s40, s40, 0
	v_add_u32_e32 v120, s40, v86
	v_lshl_add_u64 v[104:105], v[82:83], 0, s[0:1]
	v_readfirstlane_b32 s42, v120
	v_add_u32_e32 v121, 0x4000, v120
	v_lshl_add_u64 v[106:107], v[84:85], 0, s[0:1]
	v_lshl_add_u64 v[108:109], v[104:105], 0, s[18:19]
	v_add_u32_e32 v122, 0x1000, v120
	v_readfirstlane_b32 s43, v121
	s_mov_b32 m0, s42
	s_waitcnt vmcnt(0) lgkmcnt(0)
	s_barrier
	s_and_b32 s3, s3, 0x8000
	s_add_i32 s3, s3, 0
	v_add3_u32 v145, s3, v87, v88
	v_add3_u32 v210, s3, v88, v89
	v_add3_u32 v211, s3, v87, v90
	v_add3_u32 v212, s3, v89, v90
	ds_read_b128 v[154:157], v210
	ds_read_b128 v[146:149], v145 offset:16384
	ds_read_b128 v[150:153], v145 offset:18432
	ds_read_b128 v[158:161], v210 offset:2048
	ds_read_b128 v[162:165], v145 offset:20480
	ds_read_b128 v[166:169], v145 offset:22528
	ds_read_b128 v[128:131], v145 offset:24576
	ds_read_b128 v[132:135], v145 offset:26624
	ds_read_b128 v[136:139], v145 offset:28672
	ds_read_b128 v[140:143], v145 offset:30720
	v_lshl_add_u64 v[110:111], v[106:107], 0, s[20:21]
	v_add_u32_e32 v123, 0x5000, v120
	v_readfirstlane_b32 s44, v122
	global_load_lds_dwordx4 v[108:109], off
	s_mov_b32 m0, s43
	v_lshl_add_u64 v[112:113], v[104:105], 0, s[22:23]
	v_add_u32_e32 v124, 0x2000, v120
	v_readfirstlane_b32 s45, v123
	global_load_lds_dwordx4 v[110:111], off
	s_mov_b32 m0, s44
	v_lshl_add_u64 v[114:115], v[106:107], 0, s[24:25]
	v_add_u32_e32 v125, 0x6000, v120
	v_readfirstlane_b32 s53, v124
	global_load_lds_dwordx4 v[112:113], off
	s_mov_b32 m0, s45
	v_lshl_add_u64 v[116:117], v[104:105], 0, s[26:27]
	v_add_u32_e32 v126, 0x3000, v120
	v_readfirstlane_b32 s54, v125
	global_load_lds_dwordx4 v[114:115], off
	s_mov_b32 m0, s53
	v_lshl_add_u64 v[118:119], v[106:107], 0, s[28:29]
	v_add_u32_e32 v120, 0x7000, v120
	v_readfirstlane_b32 s55, v126
	global_load_lds_dwordx4 v[116:117], off
	s_mov_b32 m0, s54
	v_lshl_add_u64 v[104:105], v[104:105], 0, s[30:31]
	v_readfirstlane_b32 s56, v120
	global_load_lds_dwordx4 v[118:119], off
	s_mov_b32 m0, s55
	v_lshl_add_u64 v[106:107], v[106:107], 0, s[34:35]
	global_load_lds_dwordx4 v[104:105], off
	s_mov_b32 m0, s56
	global_load_lds_dwordx4 v[106:107], off
	ds_read_b128 v[178:181], v212
	ds_read_b128 v[170:173], v211 offset:16384
	ds_read_b128 v[174:177], v211 offset:18432
	ds_read_b128 v[182:185], v212 offset:2048
	ds_read_b128 v[186:189], v211 offset:20480
	ds_read_b128 v[190:193], v211 offset:22528
	ds_read_b128 v[194:197], v211 offset:24576
	ds_read_b128 v[198:201], v211 offset:26624
	ds_read_b128 v[202:205], v211 offset:28672
	ds_read_b128 v[206:209], v211 offset:30720
	s_add_u32 s0, s0, 0x80
	s_addc_u32 s1, s1, 0
	s_cmpk_eq_i32 s0, 0x780
	s_mov_b32 s3, s41
	s_waitcnt lgkmcnt(15)
	v_mfma_f32_16x16x32_bf16 v[60:63], v[146:149], v[154:157], v[60:63]
	v_mfma_f32_16x16x32_bf16 v[56:59], v[150:153], v[154:157], v[56:59]
	v_mfma_f32_16x16x32_bf16 v[24:27], v[146:149], v[158:161], v[24:27]
	v_mfma_f32_16x16x32_bf16 v[20:23], v[150:153], v[158:161], v[20:23]
	v_mfma_f32_16x16x32_bf16 v[52:55], v[162:165], v[154:157], v[52:55]
	v_mfma_f32_16x16x32_bf16 v[16:19], v[162:165], v[158:161], v[16:19]
	s_waitcnt lgkmcnt(14)
	v_mfma_f32_16x16x32_bf16 v[48:51], v[166:169], v[154:157], v[48:51]
	v_mfma_f32_16x16x32_bf16 v[12:15], v[166:169], v[158:161], v[12:15]
	s_waitcnt lgkmcnt(13)
	v_mfma_f32_16x16x32_bf16 v[44:47], v[128:131], v[154:157], v[44:47]
	v_mfma_f32_16x16x32_bf16 v[8:11], v[128:131], v[158:161], v[8:11]
	s_waitcnt lgkmcnt(12)
	v_mfma_f32_16x16x32_bf16 v[36:39], v[132:135], v[154:157], v[36:39]
	v_mfma_f32_16x16x32_bf16 v[4:7], v[132:135], v[158:161], v[4:7]
	s_waitcnt lgkmcnt(11)
	v_mfma_f32_16x16x32_bf16 v[32:35], v[136:139], v[154:157], v[32:35]
	v_mfma_f32_16x16x32_bf16 v[0:3], v[136:139], v[158:161], v[0:3]
	s_waitcnt lgkmcnt(10)
	v_mfma_f32_16x16x32_bf16 v[28:31], v[140:143], v[154:157], v[28:31]
	v_mfma_f32_16x16x32_bf16 v[40:43], v[140:143], v[158:161], v[40:43]
	s_waitcnt lgkmcnt(8)
	v_mfma_f32_16x16x32_bf16 v[60:63], v[170:173], v[178:181], v[60:63]
	s_waitcnt lgkmcnt(7)
	v_mfma_f32_16x16x32_bf16 v[56:59], v[174:177], v[178:181], v[56:59]
	s_waitcnt lgkmcnt(6)
	v_mfma_f32_16x16x32_bf16 v[24:27], v[170:173], v[182:185], v[24:27]
	v_mfma_f32_16x16x32_bf16 v[20:23], v[174:177], v[182:185], v[20:23]
	s_waitcnt lgkmcnt(5)
	v_mfma_f32_16x16x32_bf16 v[52:55], v[186:189], v[178:181], v[52:55]
	v_mfma_f32_16x16x32_bf16 v[16:19], v[186:189], v[182:185], v[16:19]
	s_waitcnt lgkmcnt(4)
	v_mfma_f32_16x16x32_bf16 v[48:51], v[190:193], v[178:181], v[48:51]
	v_mfma_f32_16x16x32_bf16 v[12:15], v[190:193], v[182:185], v[12:15]
	s_waitcnt lgkmcnt(3)
	v_mfma_f32_16x16x32_bf16 v[44:47], v[194:197], v[178:181], v[44:47]
	v_mfma_f32_16x16x32_bf16 v[8:11], v[194:197], v[182:185], v[8:11]
	s_waitcnt lgkmcnt(2)
	v_mfma_f32_16x16x32_bf16 v[36:39], v[198:201], v[178:181], v[36:39]
	v_mfma_f32_16x16x32_bf16 v[4:7], v[198:201], v[182:185], v[4:7]
	s_waitcnt lgkmcnt(1)
	v_mfma_f32_16x16x32_bf16 v[32:35], v[202:205], v[178:181], v[32:35]
	v_mfma_f32_16x16x32_bf16 v[0:3], v[202:205], v[182:185], v[0:3]
	s_waitcnt lgkmcnt(0)
	v_mfma_f32_16x16x32_bf16 v[28:31], v[206:209], v[178:181], v[28:31]
	v_mfma_f32_16x16x32_bf16 v[40:43], v[206:209], v[182:185], v[40:43]
	s_cbranch_scc0 .LBB0_1217
	v_add_u32_e32 v64, s40, v87
	v_add_u32_e32 v103, v64, v88
	v_add3_u32 v112, s40, v88, v89
	s_waitcnt vmcnt(0)
	s_barrier
	ds_read_b128 v[82:85], v103 offset:16384
	ds_read_b128 v[104:107], v103 offset:18432
	ds_read_b128 v[108:111], v112
	ds_read_b128 v[112:115], v112 offset:2048
	ds_read_b128 v[116:119], v103 offset:20480
	ds_read_b128 v[120:123], v103 offset:22528
	ds_read_b128 v[124:127], v103 offset:24576
	ds_read_b128 v[128:131], v103 offset:26624
	ds_read_b128 v[132:135], v103 offset:28672
	ds_read_b128 v[136:139], v103 offset:30720
	v_add_u32_e32 v64, v64, v90
	s_waitcnt lgkmcnt(7)
	v_mfma_f32_16x16x32_bf16 v[60:63], v[82:85], v[108:111], v[60:63]
	s_mul_hi_i32 s0, s2, 0x3e0f83e1
	s_lshr_b32 s1, s0, 31
	s_ashr_i32 s56, s0, 4
	v_mfma_f32_16x16x32_bf16 v[56:59], v[104:107], v[108:111], v[56:59]
	s_add_i32 s56, s56, s1
	s_cmp_gt_i32 s39, 11
	s_cselect_b64 s[0:1], -1, 0
	s_waitcnt lgkmcnt(4)
	v_mfma_f32_16x16x32_bf16 v[48:51], v[120:123], v[108:111], v[48:51]
	s_lshl_b32 s53, s2, 7
	s_cmp_lt_i32 s39, 12
	s_mul_i32 s54, s56, 0xffffdf00
	s_waitcnt lgkmcnt(3)
	v_mfma_f32_16x16x32_bf16 v[44:47], v[124:127], v[108:111], v[44:47]
	s_waitcnt lgkmcnt(2)
	v_mfma_f32_16x16x32_bf16 v[36:39], v[128:131], v[108:111], v[36:39]
	s_waitcnt lgkmcnt(1)
	v_mfma_f32_16x16x32_bf16 v[32:35], v[132:135], v[108:111], v[32:35]
	s_waitcnt lgkmcnt(0)
	v_mfma_f32_16x16x32_bf16 v[28:31], v[136:139], v[108:111], v[28:31]
	v_mfma_f32_16x16x32_bf16 v[24:27], v[82:85], v[112:115], v[24:27]
	ds_read_b128 v[82:85], v64 offset:16384
	v_mfma_f32_16x16x32_bf16 v[52:55], v[116:119], v[108:111], v[52:55]
	v_mfma_f32_16x16x32_bf16 v[20:23], v[104:107], v[112:115], v[20:23]
	v_mfma_f32_16x16x32_bf16 v[16:19], v[116:119], v[112:115], v[16:19]
	v_mfma_f32_16x16x32_bf16 v[12:15], v[120:123], v[112:115], v[12:15]
	v_mfma_f32_16x16x32_bf16 v[8:11], v[124:127], v[112:115], v[8:11]
	v_mfma_f32_16x16x32_bf16 v[4:7], v[128:131], v[112:115], v[4:7]
	v_mfma_f32_16x16x32_bf16 v[0:3], v[132:135], v[112:115], v[0:3]
	v_mfma_f32_16x16x32_bf16 v[104:107], v[136:139], v[112:115], v[40:43]
	s_nop 2
	v_add3_u32 v40, s40, v90, v89
	ds_read_b128 v[108:111], v64 offset:18432
	ds_read_b128 v[112:115], v40
	ds_read_b128 v[116:119], v40 offset:2048
	ds_read_b128 v[120:123], v64 offset:20480
	ds_read_b128 v[124:127], v64 offset:22528
	ds_read_b128 v[128:131], v64 offset:24576
	ds_read_b128 v[132:135], v64 offset:26624
	ds_read_b128 v[136:139], v64 offset:28672
	ds_read_b128 v[140:143], v64 offset:30720
	s_waitcnt lgkmcnt(7)
	v_mfma_f32_16x16x32_bf16 v[60:63], v[82:85], v[112:115], v[60:63]
	v_mfma_f32_16x16x32_bf16 v[56:59], v[108:111], v[112:115], v[56:59]
	s_waitcnt lgkmcnt(5)
	v_mfma_f32_16x16x32_bf16 v[52:55], v[120:123], v[112:115], v[52:55]
	s_waitcnt lgkmcnt(4)
	v_mfma_f32_16x16x32_bf16 v[48:51], v[124:127], v[112:115], v[48:51]
	s_waitcnt lgkmcnt(3)
	v_mfma_f32_16x16x32_bf16 v[44:47], v[128:131], v[112:115], v[44:47]
	s_waitcnt lgkmcnt(2)
	v_mfma_f32_16x16x32_bf16 v[40:43], v[132:135], v[112:115], v[36:39]
	s_waitcnt lgkmcnt(1)
	v_mfma_f32_16x16x32_bf16 v[36:39], v[136:139], v[112:115], v[32:35]
	s_waitcnt lgkmcnt(0)
	v_mfma_f32_16x16x32_bf16 v[32:35], v[140:143], v[112:115], v[28:31]
	v_mfma_f32_16x16x32_bf16 v[28:31], v[82:85], v[116:119], v[24:27]
	v_mfma_f32_16x16x32_bf16 v[24:27], v[108:111], v[116:119], v[20:23]
	v_mfma_f32_16x16x32_bf16 v[20:23], v[120:123], v[116:119], v[16:19]
	v_mfma_f32_16x16x32_bf16 v[16:19], v[124:127], v[116:119], v[12:15]
	v_mfma_f32_16x16x32_bf16 v[12:15], v[128:131], v[116:119], v[8:11]
	v_mfma_f32_16x16x32_bf16 v[8:11], v[132:135], v[116:119], v[4:7]
	v_mfma_f32_16x16x32_bf16 v[4:7], v[136:139], v[116:119], v[0:3]
	v_mfma_f32_16x16x32_bf16 v[0:3], v[140:143], v[116:119], v[104:107]
	s_cbranch_scc0 .LBB0_1224
	s_add_i32 s40, s54, s53
	v_add_u32_e32 v64, s40, v70
	v_cmp_lt_i32_e32 vcc, s48, v64
	s_and_saveexec_b64 s[2:3], vcc
	s_cbranch_execz .LBB0_1221
	v_lshl_add_u32 v64, v64, 5, v102
	v_lshlrev_b64 v[108:109], 2, v[64:65]
	v_lshl_add_u64 v[104:105], v[76:77], 0, v[108:109]
	global_load_dwordx4 v[82:85], v[104:105], off
	s_nop 0
	global_load_dwordx4 v[104:107], v[104:105], off offset:16
	v_lshl_add_u64 v[112:113], v[74:75], 0, v[108:109]
	global_load_dwordx4 v[108:111], v[112:113], off
	s_nop 0
	global_load_dwordx4 v[112:115], v[112:113], off offset:16
	s_waitcnt vmcnt(3)
	v_pk_mul_f32 v[116:117], v[54:55], v[84:85]
	v_pk_mul_f32 v[118:119], v[52:53], v[82:83]
	v_pk_mul_f32 v[120:121], v[62:63], v[84:85]
	v_pk_mul_f32 v[122:123], v[60:61], v[82:83]
	s_waitcnt vmcnt(2)
	v_pk_mul_f32 v[124:125], v[50:51], v[106:107]
	v_pk_mul_f32 v[126:127], v[48:49], v[104:105]
	v_pk_mul_f32 v[128:129], v[58:59], v[106:107]
	v_pk_mul_f32 v[130:131], v[56:57], v[104:105]
	v_pk_mul_f32 v[132:133], v[38:39], v[84:85]
	v_pk_mul_f32 v[134:135], v[36:37], v[82:83]
	v_pk_mul_f32 v[84:85], v[46:47], v[84:85]
	v_pk_mul_f32 v[82:83], v[44:45], v[82:83]
	v_pk_mul_f32 v[136:137], v[34:35], v[106:107]
	v_pk_mul_f32 v[138:139], v[32:33], v[104:105]
	v_pk_mul_f32 v[106:107], v[42:43], v[106:107]
	v_pk_mul_f32 v[104:105], v[40:41], v[104:105]
	s_waitcnt vmcnt(1)
	v_pk_fma_f32 v[62:63], v[62:63], v[110:111], v[116:117] neg_lo:[0,0,1] neg_hi:[0,0,1]
	v_pk_fma_f32 v[60:61], v[60:61], v[108:109], v[118:119] neg_lo:[0,0,1] neg_hi:[0,0,1]
	v_pk_fma_f32 v[54:55], v[54:55], v[110:111], v[120:121]
	v_pk_fma_f32 v[52:53], v[52:53], v[108:109], v[122:123]
	s_waitcnt vmcnt(0)
	v_pk_fma_f32 v[58:59], v[58:59], v[114:115], v[124:125] neg_lo:[0,0,1] neg_hi:[0,0,1]
	v_pk_fma_f32 v[56:57], v[56:57], v[112:113], v[126:127] neg_lo:[0,0,1] neg_hi:[0,0,1]
	v_pk_fma_f32 v[50:51], v[50:51], v[114:115], v[128:129]
	v_pk_fma_f32 v[48:49], v[48:49], v[112:113], v[130:131]
	v_pk_fma_f32 v[46:47], v[46:47], v[110:111], v[132:133] neg_lo:[0,0,1] neg_hi:[0,0,1]
	v_pk_fma_f32 v[44:45], v[44:45], v[108:109], v[134:135] neg_lo:[0,0,1] neg_hi:[0,0,1]
	v_pk_fma_f32 v[38:39], v[38:39], v[110:111], v[84:85]
	v_pk_fma_f32 v[36:37], v[36:37], v[108:109], v[82:83]
	v_pk_fma_f32 v[42:43], v[42:43], v[114:115], v[136:137] neg_lo:[0,0,1] neg_hi:[0,0,1]
	v_pk_fma_f32 v[40:41], v[40:41], v[112:113], v[138:139] neg_lo:[0,0,1] neg_hi:[0,0,1]
	v_pk_fma_f32 v[34:35], v[34:35], v[114:115], v[106:107]
	v_pk_fma_f32 v[32:33], v[32:33], v[112:113], v[104:105]

.LBB0_1615:
	s_add_i32 s41, s39, 0x8000
	s_and_b32 s40, s41, 0x8000
	s_add_i32 s40, s40, 0
	v_add_u32_e32 v111, s40, v82
	v_lshl_add_u64 v[76:77], v[72:73], 0, s[28:29]
	v_readfirstlane_b32 s42, v111
	v_add_u32_e32 v112, 0x4000, v111
	v_lshl_add_u64 v[78:79], v[74:75], 0, s[28:29]
	v_lshl_add_u64 v[80:81], v[76:77], 0, s[10:11]
	v_add_u32_e32 v113, 0x1000, v111
	v_readfirstlane_b32 s43, v112
	s_mov_b32 m0, s42
	s_waitcnt vmcnt(0) lgkmcnt(0)
	s_barrier
	s_and_b32 s39, s39, 0x8000
	s_add_i32 s39, s39, 0
	v_add3_u32 v145, s39, v84, v85
	v_add3_u32 v202, s39, v85, v86
	v_add3_u32 v203, s39, v84, v87
	v_add3_u32 v204, s39, v86, v87
	ds_read_b128 v[146:149], v202
	ds_read_b128 v[136:139], v145 offset:16384
	ds_read_b128 v[140:143], v145 offset:18432
	ds_read_b128 v[150:153], v202 offset:2048
	ds_read_b128 v[154:157], v145 offset:20480
	ds_read_b128 v[158:161], v145 offset:22528
	ds_read_b128 v[120:123], v145 offset:24576
	ds_read_b128 v[124:127], v145 offset:26624
	ds_read_b128 v[128:131], v145 offset:28672
	ds_read_b128 v[132:135], v145 offset:30720
	v_lshl_add_u64 v[100:101], v[78:79], 0, s[12:13]
	v_add_u32_e32 v114, 0x5000, v111
	v_readfirstlane_b32 s44, v113
	global_load_lds_dwordx4 v[80:81], off
	s_mov_b32 m0, s43
	v_lshl_add_u64 v[102:103], v[76:77], 0, s[14:15]
	v_add_u32_e32 v115, 0x2000, v111
	v_readfirstlane_b32 s45, v114
	global_load_lds_dwordx4 v[100:101], off
	s_mov_b32 m0, s44
	v_lshl_add_u64 v[104:105], v[78:79], 0, s[16:17]
	v_add_u32_e32 v116, 0x6000, v111
	v_readfirstlane_b32 s46, v115
	global_load_lds_dwordx4 v[102:103], off
	s_mov_b32 m0, s45
	v_lshl_add_u64 v[106:107], v[76:77], 0, s[18:19]
	v_add_u32_e32 v117, 0x3000, v111
	v_readfirstlane_b32 s47, v116
	global_load_lds_dwordx4 v[104:105], off
	s_mov_b32 m0, s46
	v_lshl_add_u64 v[108:109], v[78:79], 0, s[20:21]
	v_add_u32_e32 v111, 0x7000, v111
	v_readfirstlane_b32 s48, v117
	global_load_lds_dwordx4 v[106:107], off
	s_mov_b32 m0, s47
	v_lshl_add_u64 v[76:77], v[76:77], 0, s[22:23]
	v_readfirstlane_b32 s49, v111
	global_load_lds_dwordx4 v[108:109], off
	s_mov_b32 m0, s48
	v_lshl_add_u64 v[78:79], v[78:79], 0, s[24:25]
	global_load_lds_dwordx4 v[76:77], off
	s_mov_b32 m0, s49
	global_load_lds_dwordx4 v[78:79], off
	ds_read_b128 v[170:173], v204
	ds_read_b128 v[162:165], v203 offset:16384
	ds_read_b128 v[166:169], v203 offset:18432
	ds_read_b128 v[174:177], v204 offset:2048
	ds_read_b128 v[178:181], v203 offset:20480
	ds_read_b128 v[182:185], v203 offset:22528
	ds_read_b128 v[186:189], v203 offset:24576
	ds_read_b128 v[190:193], v203 offset:26624
	ds_read_b128 v[194:197], v203 offset:28672
	ds_read_b128 v[198:201], v203 offset:30720
	s_add_u32 s28, s28, 0x80
	s_addc_u32 s29, s29, 0
	s_cmpk_eq_i32 s28, 0x780
	s_mov_b32 s39, s41
	s_waitcnt lgkmcnt(15)
	v_mfma_f32_16x16x32_bf16 v[60:63], v[136:139], v[146:149], v[60:63]
	v_mfma_f32_16x16x32_bf16 v[56:59], v[140:143], v[146:149], v[56:59]
	v_mfma_f32_16x16x32_bf16 v[24:27], v[136:139], v[150:153], v[24:27]
	v_mfma_f32_16x16x32_bf16 v[20:23], v[140:143], v[150:153], v[20:23]
	v_mfma_f32_16x16x32_bf16 v[52:55], v[154:157], v[146:149], v[52:55]
	v_mfma_f32_16x16x32_bf16 v[16:19], v[154:157], v[150:153], v[16:19]
	s_waitcnt lgkmcnt(14)
	v_mfma_f32_16x16x32_bf16 v[48:51], v[158:161], v[146:149], v[48:51]
	v_mfma_f32_16x16x32_bf16 v[12:15], v[158:161], v[150:153], v[12:15]
	s_waitcnt lgkmcnt(13)
	v_mfma_f32_16x16x32_bf16 v[44:47], v[120:123], v[146:149], v[44:47]
	v_mfma_f32_16x16x32_bf16 v[8:11], v[120:123], v[150:153], v[8:11]
	s_waitcnt lgkmcnt(12)
	v_mfma_f32_16x16x32_bf16 v[40:43], v[124:127], v[146:149], v[40:43]
	v_mfma_f32_16x16x32_bf16 v[4:7], v[124:127], v[150:153], v[4:7]
	s_waitcnt lgkmcnt(11)
	v_mfma_f32_16x16x32_bf16 v[32:35], v[128:131], v[146:149], v[32:35]
	v_mfma_f32_16x16x32_bf16 v[0:3], v[128:131], v[150:153], v[0:3]
	s_waitcnt lgkmcnt(10)
	v_mfma_f32_16x16x32_bf16 v[28:31], v[132:135], v[146:149], v[28:31]
	v_mfma_f32_16x16x32_bf16 v[36:39], v[132:135], v[150:153], v[36:39]
	s_waitcnt lgkmcnt(8)
	v_mfma_f32_16x16x32_bf16 v[60:63], v[162:165], v[170:173], v[60:63]
	s_waitcnt lgkmcnt(7)
	v_mfma_f32_16x16x32_bf16 v[56:59], v[166:169], v[170:173], v[56:59]
	s_waitcnt lgkmcnt(6)
	v_mfma_f32_16x16x32_bf16 v[24:27], v[162:165], v[174:177], v[24:27]
	v_mfma_f32_16x16x32_bf16 v[20:23], v[166:169], v[174:177], v[20:23]
	s_waitcnt lgkmcnt(5)
	v_mfma_f32_16x16x32_bf16 v[52:55], v[178:181], v[170:173], v[52:55]
	v_mfma_f32_16x16x32_bf16 v[16:19], v[178:181], v[174:177], v[16:19]
	s_waitcnt lgkmcnt(4)
	v_mfma_f32_16x16x32_bf16 v[48:51], v[182:185], v[170:173], v[48:51]
	v_mfma_f32_16x16x32_bf16 v[12:15], v[182:185], v[174:177], v[12:15]
	s_waitcnt lgkmcnt(3)
	v_mfma_f32_16x16x32_bf16 v[44:47], v[186:189], v[170:173], v[44:47]
	v_mfma_f32_16x16x32_bf16 v[8:11], v[186:189], v[174:177], v[8:11]
	s_waitcnt lgkmcnt(2)
	v_mfma_f32_16x16x32_bf16 v[40:43], v[190:193], v[170:173], v[40:43]
	v_mfma_f32_16x16x32_bf16 v[4:7], v[190:193], v[174:177], v[4:7]
	s_waitcnt lgkmcnt(1)
	v_mfma_f32_16x16x32_bf16 v[32:35], v[194:197], v[170:173], v[32:35]
	v_mfma_f32_16x16x32_bf16 v[0:3], v[194:197], v[174:177], v[0:3]
	s_waitcnt lgkmcnt(0)
	v_mfma_f32_16x16x32_bf16 v[28:31], v[198:201], v[170:173], v[28:31]
	v_mfma_f32_16x16x32_bf16 v[36:39], v[198:201], v[174:177], v[36:39]
	s_cbranch_scc0 .LBB0_1615
	v_add_u32_e32 v80, s40, v84
	v_add_u32_e32 v81, v80, v85
	s_waitcnt vmcnt(0)
	s_barrier
	ds_read_b128 v[72:75], v81 offset:16384
	v_add3_u32 v99, s40, v85, v86
	ds_read_b128 v[76:79], v81 offset:18432
	ds_read_b128 v[100:103], v99
	ds_read_b128 v[104:107], v99 offset:2048
	ds_read_b128 v[108:111], v81 offset:20480
	ds_read_b128 v[112:115], v81 offset:22528
	ds_read_b128 v[116:119], v81 offset:24576
	ds_read_b128 v[120:123], v81 offset:26624
	ds_read_b128 v[124:127], v81 offset:28672
	ds_read_b128 v[128:131], v81 offset:30720
	v_add_u32_e32 v80, v80, v87
	s_waitcnt lgkmcnt(7)
	v_mfma_f32_16x16x32_bf16 v[60:63], v[72:75], v[100:103], v[60:63]
	s_lshl_b32 s38, s38, 7
	v_mfma_f32_16x16x32_bf16 v[56:59], v[76:79], v[100:103], v[56:59]
	s_waitcnt lgkmcnt(4)
	v_mfma_f32_16x16x32_bf16 v[48:51], v[112:115], v[100:103], v[48:51]
	s_waitcnt lgkmcnt(3)
	v_mfma_f32_16x16x32_bf16 v[44:47], v[116:119], v[100:103], v[44:47]
	s_waitcnt lgkmcnt(2)
	v_mfma_f32_16x16x32_bf16 v[40:43], v[120:123], v[100:103], v[40:43]
	s_waitcnt lgkmcnt(1)
	v_mfma_f32_16x16x32_bf16 v[32:35], v[124:127], v[100:103], v[32:35]
	s_waitcnt lgkmcnt(0)
	v_mfma_f32_16x16x32_bf16 v[28:31], v[128:131], v[100:103], v[28:31]
	v_mfma_f32_16x16x32_bf16 v[24:27], v[72:75], v[104:107], v[24:27]
	ds_read_b128 v[72:75], v80 offset:16384
	v_mfma_f32_16x16x32_bf16 v[52:55], v[108:111], v[100:103], v[52:55]
	v_mfma_f32_16x16x32_bf16 v[20:23], v[76:79], v[104:107], v[20:23]
	v_mfma_f32_16x16x32_bf16 v[16:19], v[108:111], v[104:107], v[16:19]
	v_mfma_f32_16x16x32_bf16 v[12:15], v[112:115], v[104:107], v[12:15]
	v_mfma_f32_16x16x32_bf16 v[8:11], v[116:119], v[104:107], v[8:11]
	v_mfma_f32_16x16x32_bf16 v[4:7], v[120:123], v[104:107], v[4:7]
	v_mfma_f32_16x16x32_bf16 v[0:3], v[124:127], v[104:107], v[0:3]
	v_mfma_f32_16x16x32_bf16 v[100:103], v[128:131], v[104:107], v[36:39]
	s_nop 2
	v_add3_u32 v36, s40, v87, v86
	ds_read_b128 v[76:79], v80 offset:18432
	ds_read_b128 v[104:107], v36
	ds_read_b128 v[108:111], v36 offset:2048
	ds_read_b128 v[128:131], v80 offset:28672
	ds_read_b128 v[132:135], v80 offset:30720
	ds_read_b128 v[112:115], v80 offset:20480
	ds_read_b128 v[116:119], v80 offset:22528
	ds_read_b128 v[120:123], v80 offset:24576
	ds_read_b128 v[124:127], v80 offset:26624
	s_waitcnt lgkmcnt(7)
	v_mfma_f32_16x16x32_bf16 v[60:63], v[72:75], v[104:107], v[60:63]
	s_waitcnt lgkmcnt(5)
	v_mfma_f32_16x16x32_bf16 v[36:39], v[128:131], v[104:107], v[32:35]
	s_waitcnt lgkmcnt(4)
	v_mfma_f32_16x16x32_bf16 v[32:35], v[132:135], v[104:107], v[28:31]
	v_mfma_f32_16x16x32_bf16 v[28:31], v[72:75], v[108:111], v[24:27]
	v_add_u32_e32 v72, s38, v83
	v_mul_hi_i32 v73, v72, s31
	v_mfma_f32_16x16x32_bf16 v[24:27], v[76:79], v[108:111], v[20:23]
	s_waitcnt lgkmcnt(3)
	v_mfma_f32_16x16x32_bf16 v[20:23], v[112:115], v[108:111], v[16:19]
	s_waitcnt lgkmcnt(2)
	v_mfma_f32_16x16x32_bf16 v[16:19], v[116:119], v[108:111], v[12:15]
	s_waitcnt lgkmcnt(1)
	v_mfma_f32_16x16x32_bf16 v[12:15], v[120:123], v[108:111], v[8:11]
	s_waitcnt lgkmcnt(0)
	v_mfma_f32_16x16x32_bf16 v[8:11], v[124:127], v[108:111], v[4:7]
	s_nop 2
	v_lshrrev_b32_e32 v4, 31, v73
	v_ashrrev_i32_e32 v5, 11, v73
	v_mfma_f32_16x16x32_bf16 v[56:59], v[76:79], v[104:107], v[56:59]
	v_add_u32_e32 v73, v5, v4
	v_mad_i32_i24 v78, v73, s33, v72
	v_lshlrev_b32_e32 v75, 13, v73
	v_mfma_f32_16x16x32_bf16 v[52:55], v[112:115], v[104:107], v[52:55]
	v_cmp_lt_i32_e32 vcc, s34, v78
	v_add3_u32 v74, v75, v78, s35
	v_mfma_f32_16x16x32_bf16 v[48:51], v[116:119], v[104:107], v[48:51]
	v_mfma_f32_16x16x32_bf16 v[44:47], v[120:123], v[104:107], v[44:47]
	v_mfma_f32_16x16x32_bf16 v[40:43], v[124:127], v[104:107], v[40:43]
	v_mfma_f32_16x16x32_bf16 v[4:7], v[128:131], v[108:111], v[0:3]
	v_mfma_f32_16x16x32_bf16 v[0:3], v[132:135], v[108:111], v[100:103]
	s_and_saveexec_b64 s[28:29], vcc
	s_xor_b64 s[28:29], exec, s[28:29]
	v_add3_u32 v72, v75, v78, s35
	s_or_saveexec_b64 s[28:29], s[28:29]
	v_mov_b64_e32 v[76:77], s[92:93]
	v_lshl_add_u32 v75, v73, 8, v78
	s_xor_b64 exec, exec, s[28:29]
	v_lshl_add_u32 v72, v73, 8, v78
	v_mov_b64_e32 v[76:77], s[2:3]
	s_or_b64 exec, exec, s[28:29]
	s_and_saveexec_b64 s[28:29], vcc
	s_xor_b64 s[28:29], exec, s[28:29]
	s_cbranch_execz .LBB0_1622
	v_add_u32_e32 v73, 3, v73
	v_mul_hi_i32_i24_e32 v79, 0x6000, v73
	v_mul_i32_i24_e32 v78, 0x6000, v73
	s_or_saveexec_b64 s[28:29], s[28:29]
	v_mov_b64_e32 v[80:81], s[92:93]
	s_xor_b64 exec, exec, s[28:29]
	s_cbranch_execnz .LBB0_1623
	s_branch .LBB0_1624

.LBB0_1759:
	s_add_i32 s36, s34, 0x8000
	s_and_b32 s35, s36, 0x8000
	s_add_i32 s35, s35, 0
	v_add_u32_e32 v111, s35, v78
	v_lshl_add_u64 v[94:95], v[74:75], 0, s[26:27]
	v_readfirstlane_b32 s37, v111
	v_add_u32_e32 v112, 0x4000, v111
	v_lshl_add_u64 v[96:97], v[76:77], 0, s[26:27]
	v_lshl_add_u64 v[98:99], v[94:95], 0, s[10:11]
	v_add_u32_e32 v113, 0x1000, v111
	v_readfirstlane_b32 s38, v112
	s_mov_b32 m0, s37
	s_waitcnt vmcnt(0) lgkmcnt(0)
	s_barrier
	s_and_b32 s34, s34, 0x8000
	s_add_i32 s34, s34, 0
	v_add3_u32 v143, s34, v80, v81
	v_add3_u32 v145, s34, v81, v82
	v_add3_u32 v230, s34, v80, v83
	v_add3_u32 v231, s34, v82, v83
	ds_read_b128 v[174:177], v145
	ds_read_b128 v[166:169], v143 offset:16384
	ds_read_b128 v[170:173], v143 offset:18432
	ds_read_b128 v[178:181], v145 offset:2048
	ds_read_b128 v[182:185], v143 offset:20480
	ds_read_b128 v[186:189], v143 offset:22528
	ds_read_b128 v[118:121], v143 offset:24576
	ds_read_b128 v[122:125], v143 offset:26624
	ds_read_b128 v[126:129], v143 offset:28672
	ds_read_b128 v[130:133], v143 offset:30720
	v_lshl_add_u64 v[100:101], v[96:97], 0, s[12:13]
	v_add_u32_e32 v114, 0x5000, v111
	v_readfirstlane_b32 s39, v113
	global_load_lds_dwordx4 v[98:99], off
	s_mov_b32 m0, s38
	v_lshl_add_u64 v[102:103], v[94:95], 0, s[14:15]
	v_add_u32_e32 v115, 0x2000, v111
	v_readfirstlane_b32 s40, v114
	global_load_lds_dwordx4 v[100:101], off
	s_mov_b32 m0, s39
	v_lshl_add_u64 v[104:105], v[96:97], 0, s[16:17]
	v_add_u32_e32 v116, 0x6000, v111
	v_readfirstlane_b32 s41, v115
	global_load_lds_dwordx4 v[102:103], off
	s_mov_b32 m0, s40
	v_lshl_add_u64 v[106:107], v[94:95], 0, s[18:19]
	v_add_u32_e32 v117, 0x3000, v111
	v_readfirstlane_b32 s42, v116
	global_load_lds_dwordx4 v[104:105], off
	s_mov_b32 m0, s41
	v_lshl_add_u64 v[108:109], v[96:97], 0, s[20:21]
	v_add_u32_e32 v111, 0x7000, v111
	v_readfirstlane_b32 s43, v117
	global_load_lds_dwordx4 v[106:107], off
	s_mov_b32 m0, s42
	v_lshl_add_u64 v[94:95], v[94:95], 0, s[22:23]
	v_readfirstlane_b32 s44, v111
	global_load_lds_dwordx4 v[108:109], off
	s_mov_b32 m0, s43
	v_lshl_add_u64 v[96:97], v[96:97], 0, s[24:25]
	global_load_lds_dwordx4 v[94:95], off
	s_mov_b32 m0, s44
	global_load_lds_dwordx4 v[96:97], off
	ds_read_b128 v[198:201], v231
	ds_read_b128 v[190:193], v230 offset:16384
	ds_read_b128 v[194:197], v230 offset:18432
	ds_read_b128 v[202:205], v231 offset:2048
	ds_read_b128 v[206:209], v230 offset:20480
	ds_read_b128 v[210:213], v230 offset:22528
	ds_read_b128 v[214:217], v230 offset:24576
	ds_read_b128 v[218:221], v230 offset:26624
	ds_read_b128 v[222:225], v230 offset:28672
	ds_read_b128 v[226:229], v230 offset:30720
	s_add_u32 s26, s26, 0x80
	s_addc_u32 s27, s27, 0
	s_cmpk_eq_i32 s26, 0x780
	s_mov_b32 s34, s36
	s_waitcnt lgkmcnt(15)
	v_mfma_f32_16x16x32_bf16 v[60:63], v[166:169], v[174:177], v[60:63]
	v_mfma_f32_16x16x32_bf16 v[56:59], v[170:173], v[174:177], v[56:59]
	v_mfma_f32_16x16x32_bf16 v[28:31], v[166:169], v[178:181], v[28:31]
	v_mfma_f32_16x16x32_bf16 v[24:27], v[170:173], v[178:181], v[24:27]
	v_mfma_f32_16x16x32_bf16 v[52:55], v[182:185], v[174:177], v[52:55]
	v_mfma_f32_16x16x32_bf16 v[20:23], v[182:185], v[178:181], v[20:23]
	s_waitcnt lgkmcnt(14)
	v_mfma_f32_16x16x32_bf16 v[48:51], v[186:189], v[174:177], v[48:51]
	v_mfma_f32_16x16x32_bf16 v[12:15], v[186:189], v[178:181], v[12:15]
	s_waitcnt lgkmcnt(13)
	v_mfma_f32_16x16x32_bf16 v[44:47], v[118:121], v[174:177], v[44:47]
	v_mfma_f32_16x16x32_bf16 v[8:11], v[118:121], v[178:181], v[8:11]
	s_waitcnt lgkmcnt(12)
	v_mfma_f32_16x16x32_bf16 v[40:43], v[122:125], v[174:177], v[40:43]
	v_mfma_f32_16x16x32_bf16 v[4:7], v[122:125], v[178:181], v[4:7]
	s_waitcnt lgkmcnt(11)
	v_mfma_f32_16x16x32_bf16 v[36:39], v[126:129], v[174:177], v[36:39]
	v_mfma_f32_16x16x32_bf16 v[0:3], v[126:129], v[178:181], v[0:3]
	s_waitcnt lgkmcnt(10)
	v_mfma_f32_16x16x32_bf16 v[32:35], v[130:133], v[174:177], v[32:35]
	v_mfma_f32_16x16x32_bf16 v[16:19], v[130:133], v[178:181], v[16:19]
	s_waitcnt lgkmcnt(8)
	v_mfma_f32_16x16x32_bf16 v[60:63], v[190:193], v[198:201], v[60:63]
	s_waitcnt lgkmcnt(7)
	v_mfma_f32_16x16x32_bf16 v[56:59], v[194:197], v[198:201], v[56:59]
	s_waitcnt lgkmcnt(6)
	v_mfma_f32_16x16x32_bf16 v[28:31], v[190:193], v[202:205], v[28:31]
	v_mfma_f32_16x16x32_bf16 v[24:27], v[194:197], v[202:205], v[24:27]
	s_waitcnt lgkmcnt(5)
	v_mfma_f32_16x16x32_bf16 v[52:55], v[206:209], v[198:201], v[52:55]
	v_mfma_f32_16x16x32_bf16 v[20:23], v[206:209], v[202:205], v[20:23]
	s_waitcnt lgkmcnt(4)
	v_mfma_f32_16x16x32_bf16 v[48:51], v[210:213], v[198:201], v[48:51]
	v_mfma_f32_16x16x32_bf16 v[12:15], v[210:213], v[202:205], v[12:15]
	s_waitcnt lgkmcnt(3)
	v_mfma_f32_16x16x32_bf16 v[44:47], v[214:217], v[198:201], v[44:47]
	v_mfma_f32_16x16x32_bf16 v[8:11], v[214:217], v[202:205], v[8:11]
	s_waitcnt lgkmcnt(2)
	v_mfma_f32_16x16x32_bf16 v[40:43], v[218:221], v[198:201], v[40:43]
	v_mfma_f32_16x16x32_bf16 v[4:7], v[218:221], v[202:205], v[4:7]
	s_waitcnt lgkmcnt(1)
	v_mfma_f32_16x16x32_bf16 v[36:39], v[222:225], v[198:201], v[36:39]
	v_mfma_f32_16x16x32_bf16 v[0:3], v[222:225], v[202:205], v[0:3]
	s_waitcnt lgkmcnt(0)
	v_mfma_f32_16x16x32_bf16 v[32:35], v[226:229], v[198:201], v[32:35]
	v_mfma_f32_16x16x32_bf16 v[16:19], v[226:229], v[202:205], v[16:19]
	s_cbranch_scc0 .LBB0_1759
	v_add_u32_e32 v138, s35, v80
	v_add_u32_e32 v126, v138, v81
	s_waitcnt vmcnt(0)
	s_barrier
	ds_read_b128 v[74:77], v126 offset:16384
	v_add3_u32 v102, s35, v81, v82
	ds_read_b128 v[94:97], v102
	ds_read_b128 v[98:101], v126 offset:18432
	ds_read_b128 v[102:105], v102 offset:2048
	ds_read_b128 v[106:109], v126 offset:20480
	ds_read_b128 v[110:113], v126 offset:22528
	ds_read_b128 v[114:117], v126 offset:24576
	ds_read_b128 v[118:121], v126 offset:26624
	v_add3_u32 v134, s35, v83, v82
	v_add_u32_e32 v142, v138, v83
	ds_read_b128 v[122:125], v126 offset:28672
	ds_read_b128 v[126:129], v126 offset:30720
	ds_read_b128 v[130:133], v134
	ds_read_b128 v[134:137], v134 offset:2048
	ds_read_b128 v[138:141], v142 offset:16384
	ds_read_b128 v[146:149], v142 offset:18432
	s_waitcnt lgkmcnt(11)
	v_mfma_f32_16x16x32_bf16 v[56:59], v[98:101], v[94:97], v[56:59]
	s_lshl_b32 s33, s33, 7
	s_lshl_b32 s26, s31, 7
	s_ashr_i32 s27, s26, 31
	v_mfma_f32_16x16x32_bf16 v[60:63], v[74:77], v[94:97], v[60:63]
	s_lshl_b64 s[26:27], s[26:27], 1
	s_add_i32 s30, s30, s28
	s_cmpk_gt_i32 s30, 0xfff
	s_waitcnt lgkmcnt(0)
	v_mfma_f32_16x16x32_bf16 v[56:59], v[146:149], v[130:133], v[56:59]
	v_mfma_f32_16x16x32_bf16 v[48:51], v[110:113], v[94:97], v[48:51]
	v_mfma_f32_16x16x32_bf16 v[52:55], v[106:109], v[94:97], v[52:55]
	s_nop 5
	v_max_f32_e32 v56, v56, v56
	v_max_f32_e32 v57, v57, v57
	v_max_f32_e32 v56, 0, v56
	v_mfma_f32_16x16x32_bf16 v[44:47], v[114:117], v[94:97], v[44:47]
	v_max_f32_e32 v57, 0, v57
	v_max_f32_e32 v59, v59, v59
	v_max_f32_e32 v59, 0, v59
	v_mfma_f32_16x16x32_bf16 v[40:43], v[118:121], v[94:97], v[40:43]
	v_mfma_f32_16x16x32_bf16 v[36:39], v[122:125], v[94:97], v[36:39]
	v_mfma_f32_16x16x32_bf16 v[32:35], v[126:129], v[94:97], v[32:35]
	ds_read_b128 v[94:97], v142 offset:20480
	ds_read_b128 v[150:153], v142 offset:22528
	ds_read_b128 v[154:157], v142 offset:24576
	ds_read_b128 v[158:161], v142 offset:26624
	v_mfma_f32_16x16x32_bf16 v[60:63], v[138:141], v[130:133], v[60:63]
	s_waitcnt lgkmcnt(2)
	v_mfma_f32_16x16x32_bf16 v[48:51], v[150:153], v[130:133], v[48:51]
	v_mfma_f32_16x16x32_bf16 v[20:23], v[106:109], v[102:105], v[20:23]
	v_mul_f32_e64 v106, v56, v56
	v_mul_f32_e64 v107, v57, v57
	v_max_f32_e32 v57, v58, v58
	s_nop 1
	v_max_f32_e32 v60, v60, v60
	v_mfma_f32_16x16x32_bf16 v[24:27], v[98:101], v[102:105], v[24:27]
	v_add_u32_e32 v100, s33, v79
	v_mov_b64_e32 v[98:99], s[0:1]
	v_max_f32_e32 v61, v61, v61
	v_max_f32_e32 v56, v62, v62
	v_max_f32_e32 v58, 0, v57
	v_max_f32_e32 v57, v63, v63
	v_mad_i64_i32 v[100:101], s[34:35], v100, s29, v[98:99]
	v_max_f32_e32 v60, 0, v60
	v_max_f32_e32 v61, 0, v61
	v_max_f32_e32 v56, 0, v56
	v_max_f32_e32 v57, 0, v57
	v_mfma_f32_16x16x32_bf16 v[52:55], v[94:97], v[130:133], v[52:55]
	v_lshl_add_u64 v[100:101], v[100:101], 0, s[26:27]
	v_pk_mul_f32 v[60:61], v[60:61], v[60:61]
	v_pk_mul_f32 v[62:63], v[56:57], v[56:57]
	v_mfma_f32_16x16x32_bf16 v[28:31], v[74:77], v[102:105], v[28:31]
	v_max_f32_e32 v48, v48, v48
	v_max_f32_e32 v49, v49, v49
	ds_read_b128 v[74:77], v142 offset:28672
	ds_read_b128 v[162:165], v142 offset:30720
	v_mfma_f32_16x16x32_bf16 v[12:15], v[110:113], v[102:105], v[12:15]
	v_lshl_add_u64 v[100:101], v[100:101], 0, v[64:65]
	v_cvt_pk_bf16_f32 v56, v60, v61
	v_cvt_pk_bf16_f32 v57, v62, v63
	v_mfma_f32_16x16x32_bf16 v[8:11], v[114:117], v[102:105], v[8:11]
	v_max_f32_e32 v48, 0, v48
	v_max_f32_e32 v49, 0, v49
	v_max_f32_e32 v52, v52, v52
	v_mfma_f32_16x16x32_bf16 v[4:7], v[118:121], v[102:105], v[4:7]
	v_max_f32_e32 v53, v53, v53
	v_max_f32_e32 v51, v51, v51
	v_max_f32_e32 v52, 0, v52
	v_mfma_f32_16x16x32_bf16 v[0:3], v[122:125], v[102:105], v[0:3]
	v_max_f32_e32 v53, 0, v53
	v_max_f32_e32 v51, 0, v51
	v_pk_mul_f32 v[52:53], v[52:53], v[52:53]
	v_mfma_f32_16x16x32_bf16 v[16:19], v[126:129], v[102:105], v[16:19]
	v_mul_f32_e64 v102, v58, v58
	v_mul_f32_e64 v103, v59, v59
	v_cvt_pk_bf16_f32 v58, v106, v107
	v_cvt_pk_bf16_f32 v59, v102, v103
	s_waitcnt lgkmcnt(2)
	v_mfma_f32_16x16x32_bf16 v[40:43], v[158:161], v[130:133], v[40:43]
	global_store_dwordx4 v[100:101], v[56:59], off
	s_nop 1
	v_pk_mul_f32 v[56:57], v[48:49], v[48:49]
	v_max_f32_e32 v49, v50, v50
	v_max_f32_e32 v48, v54, v54
	v_max_f32_e32 v50, 0, v49
	v_max_f32_e32 v49, v55, v55
	v_mfma_f32_16x16x32_bf16 v[44:47], v[154:157], v[130:133], v[44:47]
	v_max_f32_e32 v48, 0, v48
	v_max_f32_e32 v49, 0, v49
	v_pk_mul_f32 v[54:55], v[48:49], v[48:49]
	v_pk_mul_f32 v[58:59], v[50:51], v[50:51]
	v_max_f32_e32 v40, v40, v40
	v_max_f32_e32 v41, v41, v41
	s_waitcnt lgkmcnt(0)
	v_mfma_f32_16x16x32_bf16 v[32:35], v[162:165], v[130:133], v[32:35]
	v_cvt_pk_bf16_f32 v48, v52, v53
	v_cvt_pk_bf16_f32 v49, v54, v55
	v_cvt_pk_bf16_f32 v50, v56, v57
	v_cvt_pk_bf16_f32 v51, v58, v59
	v_max_f32_e32 v40, 0, v40
	v_max_f32_e32 v41, 0, v41
	global_store_dwordx4 v[100:101], v[48:51], off offset:64
	v_max_f32_e32 v44, v44, v44
	v_max_f32_e32 v45, v45, v45
	v_pk_mul_f32 v[48:49], v[40:41], v[40:41]
	v_max_f32_e32 v41, v42, v42
	v_max_f32_e32 v40, v46, v46
	v_max_f32_e32 v42, 0, v41
	v_max_f32_e32 v41, v47, v47
	v_max_f32_e32 v43, v43, v43
	v_mfma_f32_16x16x32_bf16 v[36:39], v[74:77], v[130:133], v[36:39]
	v_max_f32_e32 v44, 0, v44
	v_max_f32_e32 v45, 0, v45
	v_max_f32_e32 v40, 0, v40
	v_max_f32_e32 v41, 0, v41
	v_max_f32_e32 v43, 0, v43
	v_pk_mul_f32 v[44:45], v[44:45], v[44:45]
	v_pk_mul_f32 v[46:47], v[40:41], v[40:41]
	v_pk_mul_f32 v[50:51], v[42:43], v[42:43]
	v_max_f32_e32 v32, v32, v32
	v_max_f32_e32 v33, v33, v33
	v_mfma_f32_16x16x32_bf16 v[24:27], v[146:149], v[134:137], v[24:27]
	v_cvt_pk_bf16_f32 v40, v44, v45
	v_cvt_pk_bf16_f32 v41, v46, v47
	v_cvt_pk_bf16_f32 v42, v48, v49
	v_cvt_pk_bf16_f32 v43, v50, v51
	v_max_f32_e32 v32, 0, v32
	v_max_f32_e32 v33, 0, v33
	global_store_dwordx4 v[100:101], v[40:43], off offset:128
	v_max_f32_e32 v36, v36, v36
	v_max_f32_e32 v37, v37, v37
	v_pk_mul_f32 v[40:41], v[32:33], v[32:33]
	v_max_f32_e32 v33, v34, v34
	v_max_f32_e32 v32, v38, v38
	v_max_f32_e32 v34, 0, v33
	v_max_f32_e32 v33, v39, v39
	v_max_f32_e32 v35, v35, v35
	v_mfma_f32_16x16x32_bf16 v[28:31], v[138:141], v[134:137], v[28:31]
	v_max_f32_e32 v36, 0, v36
	v_max_f32_e32 v37, 0, v37
	v_max_f32_e32 v32, 0, v32
	v_max_f32_e32 v33, 0, v33
	v_max_f32_e32 v35, 0, v35
	v_pk_mul_f32 v[36:37], v[36:37], v[36:37]
	v_pk_mul_f32 v[38:39], v[32:33], v[32:33]
	v_pk_mul_f32 v[42:43], v[34:35], v[34:35]
	v_max_f32_e32 v24, v24, v24
	v_max_f32_e32 v25, v25, v25
	v_mfma_f32_16x16x32_bf16 v[12:15], v[150:153], v[134:137], v[12:15]
	v_cvt_pk_bf16_f32 v32, v36, v37
	v_cvt_pk_bf16_f32 v33, v38, v39
	v_cvt_pk_bf16_f32 v34, v40, v41
	v_cvt_pk_bf16_f32 v35, v42, v43
	v_max_f32_e32 v24, 0, v24
	v_max_f32_e32 v25, 0, v25
	global_store_dwordx4 v[100:101], v[32:35], off offset:192
	v_max_f32_e32 v28, v28, v28
	v_max_f32_e32 v29, v29, v29
	v_pk_mul_f32 v[34:35], v[24:25], v[24:25]
	v_max_f32_e32 v25, v26, v26
	v_add_u32_e32 v32, s33, v84
	v_max_f32_e32 v24, v30, v30
	v_max_f32_e32 v26, 0, v25
	v_max_f32_e32 v25, v31, v31
	v_max_f32_e32 v27, v27, v27
	v_mfma_f32_16x16x32_bf16 v[20:23], v[94:97], v[134:137], v[20:23]
	v_mad_i64_i32 v[32:33], s[34:35], v32, s29, v[98:99]
	v_max_f32_e32 v28, 0, v28
	v_max_f32_e32 v29, 0, v29
	v_max_f32_e32 v24, 0, v24
	v_max_f32_e32 v25, 0, v25
	v_max_f32_e32 v27, 0, v27
	v_lshl_add_u64 v[32:33], v[32:33], 0, s[26:27]
	v_pk_mul_f32 v[28:29], v[28:29], v[28:29]
	v_pk_mul_f32 v[30:31], v[24:25], v[24:25]
	v_pk_mul_f32 v[36:37], v[26:27], v[26:27]
	v_max_f32_e32 v12, v12, v12
	v_max_f32_e32 v13, v13, v13
	v_mfma_f32_16x16x32_bf16 v[4:7], v[158:161], v[134:137], v[4:7]
	v_lshl_add_u64 v[32:33], v[32:33], 0, v[64:65]
	v_cvt_pk_bf16_f32 v24, v28, v29
	v_cvt_pk_bf16_f32 v25, v30, v31
	v_cvt_pk_bf16_f32 v26, v34, v35
	v_cvt_pk_bf16_f32 v27, v36, v37
	v_max_f32_e32 v12, 0, v12
	v_max_f32_e32 v13, 0, v13
	global_store_dwordx4 v[32:33], v[24:27], off
	v_max_f32_e32 v20, v20, v20
	v_max_f32_e32 v21, v21, v21
	v_pk_mul_f32 v[24:25], v[12:13], v[12:13]
	v_max_f32_e32 v13, v14, v14
	v_max_f32_e32 v12, v22, v22
	v_max_f32_e32 v14, 0, v13
	v_max_f32_e32 v13, v23, v23
	v_max_f32_e32 v15, v15, v15
	v_mfma_f32_16x16x32_bf16 v[8:11], v[154:157], v[134:137], v[8:11]
	v_max_f32_e32 v20, 0, v20
	v_max_f32_e32 v21, 0, v21
	v_max_f32_e32 v12, 0, v12
	v_max_f32_e32 v13, 0, v13
	v_max_f32_e32 v15, 0, v15
	v_pk_mul_f32 v[20:21], v[20:21], v[20:21]
	v_pk_mul_f32 v[22:23], v[12:13], v[12:13]
	v_pk_mul_f32 v[26:27], v[14:15], v[14:15]
	v_max_f32_e32 v4, v4, v4
	v_max_f32_e32 v5, v5, v5
	v_cvt_pk_bf16_f32 v12, v20, v21
	v_cvt_pk_bf16_f32 v13, v22, v23
	v_cvt_pk_bf16_f32 v14, v24, v25
	v_cvt_pk_bf16_f32 v15, v26, v27
	v_max_f32_e32 v4, 0, v4
	v_max_f32_e32 v5, 0, v5
	global_store_dwordx4 v[32:33], v[12:15], off offset:64
	v_mfma_f32_16x16x32_bf16 v[0:3], v[74:77], v[134:137], v[0:3]
	v_max_f32_e32 v8, v8, v8
	v_pk_mul_f32 v[12:13], v[4:5], v[4:5]
	v_max_f32_e32 v5, v6, v6
	v_mfma_f32_16x16x32_bf16 v[16:19], v[162:165], v[134:137], v[16:19]
	v_max_f32_e32 v9, v9, v9
	v_max_f32_e32 v4, v10, v10
	v_max_f32_e32 v6, 0, v5
	v_max_f32_e32 v5, v11, v11
	v_max_f32_e32 v7, v7, v7
	v_max_f32_e32 v8, 0, v8
	v_max_f32_e32 v9, 0, v9
	v_max_f32_e32 v4, 0, v4
	v_max_f32_e32 v5, 0, v5
	v_max_f32_e32 v7, 0, v7
	v_pk_mul_f32 v[8:9], v[8:9], v[8:9]
	v_pk_mul_f32 v[10:11], v[4:5], v[4:5]
	v_pk_mul_f32 v[14:15], v[6:7], v[6:7]
	v_cvt_pk_bf16_f32 v4, v8, v9
	v_cvt_pk_bf16_f32 v5, v10, v11
	v_cvt_pk_bf16_f32 v6, v12, v13
	v_cvt_pk_bf16_f32 v7, v14, v15
	global_store_dwordx4 v[32:33], v[4:7], off offset:128
	v_max_f32_e32 v0, v0, v0
	v_max_f32_e32 v1, v1, v1
	v_max_f32_e32 v4, v16, v16
	v_max_f32_e32 v5, v17, v17
	v_max_f32_e32 v2, v2, v2
	v_max_f32_e32 v6, v18, v18
	v_max_f32_e32 v3, v3, v3
	v_max_f32_e32 v7, v19, v19
	v_max_f32_e32 v0, 0, v0
	v_max_f32_e32 v4, 0, v4
	v_max_f32_e32 v1, 0, v1
	v_max_f32_e32 v5, 0, v5
	v_max_f32_e32 v2, 0, v2
	v_max_f32_e32 v6, 0, v6
	v_max_f32_e32 v3, 0, v3
	v_max_f32_e32 v7, 0, v7
	v_pk_mul_f32 v[0:1], v[0:1], v[0:1]
	v_pk_mul_f32 v[4:5], v[4:5], v[4:5]
	v_pk_mul_f32 v[2:3], v[2:3], v[2:3]
	v_pk_mul_f32 v[6:7], v[6:7], v[6:7]
	v_cvt_pk_bf16_f32 v0, v0, v1
	v_cvt_pk_bf16_f32 v1, v2, v3
	v_cvt_pk_bf16_f32 v2, v4, v5
	v_cvt_pk_bf16_f32 v3, v6, v7
	global_store_dwordx4 v[32:33], v[0:3], off offset:192
	s_cbranch_scc0 .LBB0_1754

.LBB0_1824:
	s_add_i32 s41, s39, 0x8000
	s_and_b32 s40, s41, 0x8000
	s_add_i32 s40, s40, 0
	v_add_u32_e32 v111, s40, v82
	v_lshl_add_u64 v[76:77], v[72:73], 0, s[28:29]
	v_readfirstlane_b32 s42, v111
	v_add_u32_e32 v112, 0x4000, v111
	v_lshl_add_u64 v[78:79], v[74:75], 0, s[28:29]
	v_lshl_add_u64 v[80:81], v[76:77], 0, s[10:11]
	v_add_u32_e32 v113, 0x1000, v111
	v_readfirstlane_b32 s43, v112
	s_mov_b32 m0, s42
	s_waitcnt vmcnt(0) lgkmcnt(0)
	s_barrier
	s_and_b32 s39, s39, 0x8000
	s_add_i32 s39, s39, 0
	v_add3_u32 v145, s39, v84, v85
	v_add3_u32 v202, s39, v85, v86
	v_add3_u32 v203, s39, v84, v87
	v_add3_u32 v204, s39, v86, v87
	ds_read_b128 v[146:149], v202
	ds_read_b128 v[136:139], v145 offset:16384
	ds_read_b128 v[140:143], v145 offset:18432
	ds_read_b128 v[150:153], v202 offset:2048
	ds_read_b128 v[154:157], v145 offset:20480
	ds_read_b128 v[158:161], v145 offset:22528
	ds_read_b128 v[120:123], v145 offset:24576
	ds_read_b128 v[124:127], v145 offset:26624
	ds_read_b128 v[128:131], v145 offset:28672
	ds_read_b128 v[132:135], v145 offset:30720
	v_lshl_add_u64 v[100:101], v[78:79], 0, s[12:13]
	v_add_u32_e32 v114, 0x5000, v111
	v_readfirstlane_b32 s44, v113
	global_load_lds_dwordx4 v[80:81], off
	s_mov_b32 m0, s43
	v_lshl_add_u64 v[102:103], v[76:77], 0, s[14:15]
	v_add_u32_e32 v115, 0x2000, v111
	v_readfirstlane_b32 s45, v114
	global_load_lds_dwordx4 v[100:101], off
	s_mov_b32 m0, s44
	v_lshl_add_u64 v[104:105], v[78:79], 0, s[16:17]
	v_add_u32_e32 v116, 0x6000, v111
	v_readfirstlane_b32 s46, v115
	global_load_lds_dwordx4 v[102:103], off
	s_mov_b32 m0, s45
	v_lshl_add_u64 v[106:107], v[76:77], 0, s[18:19]
	v_add_u32_e32 v117, 0x3000, v111
	v_readfirstlane_b32 s47, v116
	global_load_lds_dwordx4 v[104:105], off
	s_mov_b32 m0, s46
	v_lshl_add_u64 v[108:109], v[78:79], 0, s[20:21]
	v_add_u32_e32 v111, 0x7000, v111
	v_readfirstlane_b32 s48, v117
	global_load_lds_dwordx4 v[106:107], off
	s_mov_b32 m0, s47
	v_lshl_add_u64 v[76:77], v[76:77], 0, s[22:23]
	v_readfirstlane_b32 s49, v111
	global_load_lds_dwordx4 v[108:109], off
	s_mov_b32 m0, s48
	v_lshl_add_u64 v[78:79], v[78:79], 0, s[24:25]
	global_load_lds_dwordx4 v[76:77], off
	s_mov_b32 m0, s49
	global_load_lds_dwordx4 v[78:79], off
	ds_read_b128 v[170:173], v204
	ds_read_b128 v[162:165], v203 offset:16384
	ds_read_b128 v[166:169], v203 offset:18432
	ds_read_b128 v[174:177], v204 offset:2048
	ds_read_b128 v[178:181], v203 offset:20480
	ds_read_b128 v[182:185], v203 offset:22528
	ds_read_b128 v[186:189], v203 offset:24576
	ds_read_b128 v[190:193], v203 offset:26624
	ds_read_b128 v[194:197], v203 offset:28672
	ds_read_b128 v[198:201], v203 offset:30720
	s_add_u32 s28, s28, 0x80
	s_addc_u32 s29, s29, 0
	s_cmpk_eq_i32 s28, 0x1f80
	s_mov_b32 s39, s41
	s_waitcnt lgkmcnt(15)
	v_mfma_f32_16x16x32_bf16 v[60:63], v[136:139], v[146:149], v[60:63]
	v_mfma_f32_16x16x32_bf16 v[56:59], v[140:143], v[146:149], v[56:59]
	v_mfma_f32_16x16x32_bf16 v[24:27], v[136:139], v[150:153], v[24:27]
	v_mfma_f32_16x16x32_bf16 v[20:23], v[140:143], v[150:153], v[20:23]
	v_mfma_f32_16x16x32_bf16 v[52:55], v[154:157], v[146:149], v[52:55]
	v_mfma_f32_16x16x32_bf16 v[16:19], v[154:157], v[150:153], v[16:19]
	s_waitcnt lgkmcnt(14)
	v_mfma_f32_16x16x32_bf16 v[48:51], v[158:161], v[146:149], v[48:51]
	v_mfma_f32_16x16x32_bf16 v[12:15], v[158:161], v[150:153], v[12:15]
	s_waitcnt lgkmcnt(13)
	v_mfma_f32_16x16x32_bf16 v[44:47], v[120:123], v[146:149], v[44:47]
	v_mfma_f32_16x16x32_bf16 v[8:11], v[120:123], v[150:153], v[8:11]
	s_waitcnt lgkmcnt(12)
	v_mfma_f32_16x16x32_bf16 v[40:43], v[124:127], v[146:149], v[40:43]
	v_mfma_f32_16x16x32_bf16 v[4:7], v[124:127], v[150:153], v[4:7]
	s_waitcnt lgkmcnt(11)
	v_mfma_f32_16x16x32_bf16 v[32:35], v[128:131], v[146:149], v[32:35]
	v_mfma_f32_16x16x32_bf16 v[0:3], v[128:131], v[150:153], v[0:3]
	s_waitcnt lgkmcnt(10)
	v_mfma_f32_16x16x32_bf16 v[28:31], v[132:135], v[146:149], v[28:31]
	v_mfma_f32_16x16x32_bf16 v[36:39], v[132:135], v[150:153], v[36:39]
	s_waitcnt lgkmcnt(8)
	v_mfma_f32_16x16x32_bf16 v[60:63], v[162:165], v[170:173], v[60:63]
	s_waitcnt lgkmcnt(7)
	v_mfma_f32_16x16x32_bf16 v[56:59], v[166:169], v[170:173], v[56:59]
	s_waitcnt lgkmcnt(6)
	v_mfma_f32_16x16x32_bf16 v[24:27], v[162:165], v[174:177], v[24:27]
	v_mfma_f32_16x16x32_bf16 v[20:23], v[166:169], v[174:177], v[20:23]
	s_waitcnt lgkmcnt(5)
	v_mfma_f32_16x16x32_bf16 v[52:55], v[178:181], v[170:173], v[52:55]
	v_mfma_f32_16x16x32_bf16 v[16:19], v[178:181], v[174:177], v[16:19]
	s_waitcnt lgkmcnt(4)
	v_mfma_f32_16x16x32_bf16 v[48:51], v[182:185], v[170:173], v[48:51]
	v_mfma_f32_16x16x32_bf16 v[12:15], v[182:185], v[174:177], v[12:15]
	s_waitcnt lgkmcnt(3)
	v_mfma_f32_16x16x32_bf16 v[44:47], v[186:189], v[170:173], v[44:47]
	v_mfma_f32_16x16x32_bf16 v[8:11], v[186:189], v[174:177], v[8:11]
	s_waitcnt lgkmcnt(2)
	v_mfma_f32_16x16x32_bf16 v[40:43], v[190:193], v[170:173], v[40:43]
	v_mfma_f32_16x16x32_bf16 v[4:7], v[190:193], v[174:177], v[4:7]
	s_waitcnt lgkmcnt(1)
	v_mfma_f32_16x16x32_bf16 v[32:35], v[194:197], v[170:173], v[32:35]
	v_mfma_f32_16x16x32_bf16 v[0:3], v[194:197], v[174:177], v[0:3]
	s_waitcnt lgkmcnt(0)
	v_mfma_f32_16x16x32_bf16 v[28:31], v[198:201], v[170:173], v[28:31]
	v_mfma_f32_16x16x32_bf16 v[36:39], v[198:201], v[174:177], v[36:39]
	s_cbranch_scc0 .LBB0_1824
	v_add_u32_e32 v80, s40, v84
	v_add_u32_e32 v81, v80, v85
	s_waitcnt vmcnt(0)
	s_barrier
	ds_read_b128 v[72:75], v81 offset:16384
	v_add3_u32 v99, s40, v85, v86
	ds_read_b128 v[76:79], v81 offset:18432
	ds_read_b128 v[100:103], v99
	ds_read_b128 v[104:107], v99 offset:2048
	ds_read_b128 v[108:111], v81 offset:20480
	ds_read_b128 v[112:115], v81 offset:22528
	ds_read_b128 v[116:119], v81 offset:24576
	ds_read_b128 v[120:123], v81 offset:26624
	ds_read_b128 v[124:127], v81 offset:28672
	ds_read_b128 v[128:131], v81 offset:30720
	v_add_u32_e32 v80, v80, v87
	s_waitcnt lgkmcnt(7)
	v_mfma_f32_16x16x32_bf16 v[60:63], v[72:75], v[100:103], v[60:63]
	s_lshl_b32 s38, s38, 7
	v_mfma_f32_16x16x32_bf16 v[56:59], v[76:79], v[100:103], v[56:59]
	s_waitcnt lgkmcnt(4)
	v_mfma_f32_16x16x32_bf16 v[48:51], v[112:115], v[100:103], v[48:51]
	s_waitcnt lgkmcnt(3)
	v_mfma_f32_16x16x32_bf16 v[44:47], v[116:119], v[100:103], v[44:47]
	s_waitcnt lgkmcnt(2)
	v_mfma_f32_16x16x32_bf16 v[40:43], v[120:123], v[100:103], v[40:43]
	s_waitcnt lgkmcnt(1)
	v_mfma_f32_16x16x32_bf16 v[32:35], v[124:127], v[100:103], v[32:35]
	s_waitcnt lgkmcnt(0)
	v_mfma_f32_16x16x32_bf16 v[28:31], v[128:131], v[100:103], v[28:31]
	v_mfma_f32_16x16x32_bf16 v[24:27], v[72:75], v[104:107], v[24:27]
	ds_read_b128 v[72:75], v80 offset:16384
	v_mfma_f32_16x16x32_bf16 v[52:55], v[108:111], v[100:103], v[52:55]
	v_mfma_f32_16x16x32_bf16 v[20:23], v[76:79], v[104:107], v[20:23]
	v_mfma_f32_16x16x32_bf16 v[16:19], v[108:111], v[104:107], v[16:19]
	v_mfma_f32_16x16x32_bf16 v[12:15], v[112:115], v[104:107], v[12:15]
	v_mfma_f32_16x16x32_bf16 v[8:11], v[116:119], v[104:107], v[8:11]
	v_mfma_f32_16x16x32_bf16 v[4:7], v[120:123], v[104:107], v[4:7]
	v_mfma_f32_16x16x32_bf16 v[0:3], v[124:127], v[104:107], v[0:3]
	v_mfma_f32_16x16x32_bf16 v[100:103], v[128:131], v[104:107], v[36:39]
	s_nop 2
	v_add3_u32 v36, s40, v87, v86
	ds_read_b128 v[76:79], v80 offset:18432
	ds_read_b128 v[104:107], v36
	ds_read_b128 v[108:111], v36 offset:2048
	ds_read_b128 v[128:131], v80 offset:28672
	ds_read_b128 v[132:135], v80 offset:30720
	ds_read_b128 v[112:115], v80 offset:20480
	ds_read_b128 v[116:119], v80 offset:22528
	ds_read_b128 v[120:123], v80 offset:24576
	ds_read_b128 v[124:127], v80 offset:26624
	s_waitcnt lgkmcnt(7)
	v_mfma_f32_16x16x32_bf16 v[60:63], v[72:75], v[104:107], v[60:63]
	s_waitcnt lgkmcnt(5)
	v_mfma_f32_16x16x32_bf16 v[36:39], v[128:131], v[104:107], v[32:35]
	s_waitcnt lgkmcnt(4)
	v_mfma_f32_16x16x32_bf16 v[32:35], v[132:135], v[104:107], v[28:31]
	v_mfma_f32_16x16x32_bf16 v[28:31], v[72:75], v[108:111], v[24:27]
	v_add_u32_e32 v72, s38, v83
	v_mul_hi_i32 v73, v72, s31
	v_mfma_f32_16x16x32_bf16 v[24:27], v[76:79], v[108:111], v[20:23]
	s_waitcnt lgkmcnt(3)
	v_mfma_f32_16x16x32_bf16 v[20:23], v[112:115], v[108:111], v[16:19]
	s_waitcnt lgkmcnt(2)
	v_mfma_f32_16x16x32_bf16 v[16:19], v[116:119], v[108:111], v[12:15]
	s_waitcnt lgkmcnt(1)
	v_mfma_f32_16x16x32_bf16 v[12:15], v[120:123], v[108:111], v[8:11]
	s_waitcnt lgkmcnt(0)
	v_mfma_f32_16x16x32_bf16 v[8:11], v[124:127], v[108:111], v[4:7]
	s_nop 2
	v_lshrrev_b32_e32 v4, 31, v73
	v_ashrrev_i32_e32 v5, 11, v73
	v_mfma_f32_16x16x32_bf16 v[56:59], v[76:79], v[104:107], v[56:59]
	v_add_u32_e32 v73, v5, v4
	v_mad_i32_i24 v78, v73, s33, v72
	v_lshlrev_b32_e32 v75, 13, v73
	v_mfma_f32_16x16x32_bf16 v[52:55], v[112:115], v[104:107], v[52:55]
	v_cmp_lt_i32_e32 vcc, s34, v78
	v_add3_u32 v74, v75, v78, s35
	v_mfma_f32_16x16x32_bf16 v[48:51], v[116:119], v[104:107], v[48:51]
	v_mfma_f32_16x16x32_bf16 v[44:47], v[120:123], v[104:107], v[44:47]
	v_mfma_f32_16x16x32_bf16 v[40:43], v[124:127], v[104:107], v[40:43]
	v_mfma_f32_16x16x32_bf16 v[4:7], v[128:131], v[108:111], v[0:3]
	v_mfma_f32_16x16x32_bf16 v[0:3], v[132:135], v[108:111], v[100:103]
	s_and_saveexec_b64 s[28:29], vcc
	s_xor_b64 s[28:29], exec, s[28:29]
	v_add3_u32 v72, v75, v78, s35
	s_or_saveexec_b64 s[28:29], s[28:29]
	v_mov_b64_e32 v[76:77], s[92:93]
	v_lshl_add_u32 v75, v73, 8, v78
	s_xor_b64 exec, exec, s[28:29]
	v_lshl_add_u32 v72, v73, 8, v78
	v_mov_b64_e32 v[76:77], s[2:3]
	s_or_b64 exec, exec, s[28:29]
	s_and_saveexec_b64 s[28:29], vcc
	s_xor_b64 s[28:29], exec, s[28:29]
	s_cbranch_execz .LBB0_1831
	v_add_u32_e32 v73, 3, v73
	v_mul_hi_i32_i24_e32 v79, 0x6000, v73
	v_mul_i32_i24_e32 v78, 0x6000, v73
	s_or_saveexec_b64 s[28:29], s[28:29]
	v_mov_b64_e32 v[80:81], s[92:93]
	s_xor_b64 exec, exec, s[28:29]
	s_cbranch_execnz .LBB0_1832
	s_branch .LBB0_1833
